# removed all s_setprio flips in GEMM phases (kept attention)
# speedup vs baseline: 1.0064x; 1.0064x over previous
.LBB0_86:
	ds_read_b128 v[154:157], v150
	ds_read_b128 v[158:161], v150 offset:1024
	ds_read_b128 v[162:165], v150 offset:2048
	ds_read_b128 v[166:169], v150 offset:3072
	ds_read_b128 v[170:173], v151
	ds_read_b128 v[174:177], v151 offset:1024
	ds_read_b128 v[178:181], v151 offset:2048
	ds_read_b128 v[182:185], v151 offset:3072
	s_add_u32 s30, s28, 0xfffc0080
	s_addc_u32 s31, s29, -1
	s_cmp_eq_u32 s53, 12
	s_cselect_b32 s35, s10, s31
	s_cselect_b32 s34, s19, s30
	s_cselect_b32 s31, s17, s52
	s_cselect_b32 s30, s20, s21
	v_lshl_add_u64 v[146:147], s[28:29], 0, v[138:139]
	s_add_i32 m0, s27, 0xc000
	ds_read_b128 v[186:189], v152
	ds_read_b128 v[190:193], v152 offset:1024
	ds_read_b128 v[194:197], v152 offset:2048
	ds_read_b128 v[198:201], v152 offset:3072
	ds_read_b128 v[202:205], v152 offset:4096
	ds_read_b128 v[206:209], v152 offset:5120
	ds_read_b128 v[210:213], v152 offset:6144
	ds_read_b128 v[214:217], v152 offset:7168
	global_load_lds_dwordx4 v[146:147], off
	v_lshl_add_u64 v[146:147], s[28:29], 0, v[140:141]
	s_add_i32 m0, s27, 0xe000
	s_nop 0
	global_load_lds_dwordx4 v[146:147], off
	s_waitcnt vmcnt(8)
	s_waitcnt lgkmcnt(0)
	s_barrier
	s_waitcnt lgkmcnt(0)
	v_mfma_f32_16x16x32_bf16 v[126:129], v[154:157], v[186:189], v[126:129]
	v_mfma_f32_16x16x32_bf16 v[122:125], v[162:165], v[186:189], v[122:125]
	v_mfma_f32_16x16x32_bf16 v[110:113], v[154:157], v[194:197], v[110:113]
	v_mfma_f32_16x16x32_bf16 v[106:109], v[162:165], v[194:197], v[106:109]
	v_mfma_f32_16x16x32_bf16 v[94:97], v[154:157], v[202:205], v[94:97]
	v_mfma_f32_16x16x32_bf16 v[90:93], v[162:165], v[202:205], v[90:93]
	v_mfma_f32_16x16x32_bf16 v[78:81], v[154:157], v[210:213], v[78:81]
	v_mfma_f32_16x16x32_bf16 v[74:77], v[162:165], v[210:213], v[74:77]
	v_mfma_f32_16x16x32_bf16 v[126:129], v[158:161], v[190:193], v[126:129]
	v_mfma_f32_16x16x32_bf16 v[122:125], v[166:169], v[190:193], v[122:125]
	v_mfma_f32_16x16x32_bf16 v[110:113], v[158:161], v[198:201], v[110:113]
	v_mfma_f32_16x16x32_bf16 v[106:109], v[166:169], v[198:201], v[106:109]
	v_mfma_f32_16x16x32_bf16 v[94:97], v[158:161], v[206:209], v[94:97]
	v_mfma_f32_16x16x32_bf16 v[90:93], v[166:169], v[206:209], v[90:93]
	v_mfma_f32_16x16x32_bf16 v[78:81], v[158:161], v[214:217], v[78:81]
	v_mfma_f32_16x16x32_bf16 v[74:77], v[166:169], v[214:217], v[74:77]
	v_mfma_f32_16x16x32_bf16 v[118:121], v[170:173], v[186:189], v[118:121]
	v_mfma_f32_16x16x32_bf16 v[114:117], v[178:181], v[186:189], v[114:117]
	v_mfma_f32_16x16x32_bf16 v[102:105], v[170:173], v[194:197], v[102:105]
	v_mfma_f32_16x16x32_bf16 v[98:101], v[178:181], v[194:197], v[98:101]
	v_mfma_f32_16x16x32_bf16 v[86:89], v[170:173], v[202:205], v[86:89]
	v_mfma_f32_16x16x32_bf16 v[82:85], v[178:181], v[202:205], v[82:85]
	v_mfma_f32_16x16x32_bf16 v[70:73], v[170:173], v[210:213], v[70:73]
	v_mfma_f32_16x16x32_bf16 v[66:69], v[178:181], v[210:213], v[66:69]
	v_mfma_f32_16x16x32_bf16 v[118:121], v[174:177], v[190:193], v[118:121]
	v_mfma_f32_16x16x32_bf16 v[114:117], v[182:185], v[190:193], v[114:117]
	v_mfma_f32_16x16x32_bf16 v[102:105], v[174:177], v[198:201], v[102:105]
	v_mfma_f32_16x16x32_bf16 v[98:101], v[182:185], v[198:201], v[98:101]
	v_mfma_f32_16x16x32_bf16 v[86:89], v[174:177], v[206:209], v[86:89]
	v_mfma_f32_16x16x32_bf16 v[82:85], v[182:185], v[206:209], v[82:85]
	v_mfma_f32_16x16x32_bf16 v[70:73], v[174:177], v[214:217], v[70:73]
	v_mfma_f32_16x16x32_bf16 v[66:69], v[182:185], v[214:217], v[66:69]
	s_barrier
	s_add_i32 s54, s48, s38
	v_lshl_add_u64 v[146:147], s[30:31], 0, v[134:135]
	s_mov_b32 m0, s54
	ds_read_b128 v[186:189], v152 offset:16384
	ds_read_b128 v[190:193], v152 offset:17408
	ds_read_b128 v[194:197], v152 offset:18432
	ds_read_b128 v[198:201], v152 offset:19456
	ds_read_b128 v[202:205], v152 offset:20480
	ds_read_b128 v[206:209], v152 offset:21504
	ds_read_b128 v[210:213], v152 offset:22528
	ds_read_b128 v[214:217], v152 offset:23552
	global_load_lds_dwordx4 v[146:147], off
	s_add_i32 m0, s54, 0x2000
	s_add_u32 s54, s30, 0x40000
	v_lshl_add_u64 v[218:219], s[30:31], 0, v[130:131]
	s_addc_u32 s55, s31, 0
	s_add_i32 s56, s49, s38
	global_load_lds_dwordx4 v[218:219], off
	v_lshl_add_u64 v[220:221], s[54:55], 0, v[134:135]
	s_mov_b32 m0, s56
	v_lshl_add_u64 v[222:223], s[34:35], 0, v[132:133]
	global_load_lds_dwordx4 v[220:221], off
	v_lshl_add_u64 v[220:221], s[54:55], 0, v[130:131]
	s_add_i32 m0, s56, 0x2000
	s_nop 0
	global_load_lds_dwordx4 v[220:221], off
	v_lshl_add_u64 v[220:221], s[34:35], 0, v[136:137]
	s_mov_b32 m0, s27
	s_nop 0
	global_load_lds_dwordx4 v[220:221], off
	s_mov_b32 m0, s41
	s_nop 0
	global_load_lds_dwordx4 v[222:223], off
	s_waitcnt vmcnt(8)
	s_waitcnt lgkmcnt(0)
	s_barrier
	s_waitcnt lgkmcnt(0)
	v_mfma_f32_16x16x32_bf16 v[62:65], v[154:157], v[186:189], v[62:65]
	v_mfma_f32_16x16x32_bf16 v[58:61], v[162:165], v[186:189], v[58:61]
	v_mfma_f32_16x16x32_bf16 v[46:49], v[154:157], v[194:197], v[46:49]
	v_mfma_f32_16x16x32_bf16 v[42:45], v[162:165], v[194:197], v[42:45]
	v_mfma_f32_16x16x32_bf16 v[30:33], v[154:157], v[202:205], v[30:33]
	v_mfma_f32_16x16x32_bf16 v[26:29], v[162:165], v[202:205], v[26:29]
	v_mfma_f32_16x16x32_bf16 v[14:17], v[154:157], v[210:213], v[14:17]
	v_mfma_f32_16x16x32_bf16 v[10:13], v[162:165], v[210:213], v[10:13]
	v_mfma_f32_16x16x32_bf16 v[62:65], v[158:161], v[190:193], v[62:65]
	v_mfma_f32_16x16x32_bf16 v[58:61], v[166:169], v[190:193], v[58:61]
	v_mfma_f32_16x16x32_bf16 v[46:49], v[158:161], v[198:201], v[46:49]
	v_mfma_f32_16x16x32_bf16 v[42:45], v[166:169], v[198:201], v[42:45]
	v_mfma_f32_16x16x32_bf16 v[30:33], v[158:161], v[206:209], v[30:33]
	v_mfma_f32_16x16x32_bf16 v[26:29], v[166:169], v[206:209], v[26:29]
	v_mfma_f32_16x16x32_bf16 v[14:17], v[158:161], v[214:217], v[14:17]
	v_mfma_f32_16x16x32_bf16 v[10:13], v[166:169], v[214:217], v[10:13]
	v_mfma_f32_16x16x32_bf16 v[54:57], v[170:173], v[186:189], v[54:57]
	v_mfma_f32_16x16x32_bf16 v[50:53], v[178:181], v[186:189], v[50:53]
	v_mfma_f32_16x16x32_bf16 v[38:41], v[170:173], v[194:197], v[38:41]
	v_mfma_f32_16x16x32_bf16 v[34:37], v[178:181], v[194:197], v[34:37]
	v_mfma_f32_16x16x32_bf16 v[22:25], v[170:173], v[202:205], v[22:25]
	v_mfma_f32_16x16x32_bf16 v[18:21], v[178:181], v[202:205], v[18:21]
	v_mfma_f32_16x16x32_bf16 v[6:9], v[170:173], v[210:213], v[6:9]
	v_mfma_f32_16x16x32_bf16 v[2:5], v[178:181], v[210:213], v[2:5]
	v_mfma_f32_16x16x32_bf16 v[54:57], v[174:177], v[190:193], v[54:57]
	v_mfma_f32_16x16x32_bf16 v[50:53], v[182:185], v[190:193], v[50:53]
	v_mfma_f32_16x16x32_bf16 v[38:41], v[174:177], v[198:201], v[38:41]
	v_mfma_f32_16x16x32_bf16 v[34:37], v[182:185], v[198:201], v[34:37]
	v_mfma_f32_16x16x32_bf16 v[22:25], v[174:177], v[206:209], v[22:25]
	v_mfma_f32_16x16x32_bf16 v[18:21], v[182:185], v[206:209], v[18:21]
	v_mfma_f32_16x16x32_bf16 v[6:9], v[174:177], v[214:217], v[6:9]
	v_mfma_f32_16x16x32_bf16 v[2:5], v[182:185], v[214:217], v[2:5]
	s_barrier
	s_add_i32 s54, 0, 0x18000
	v_add_u32_e32 v153, s54, v148
	s_add_i32 s55, 0, 0x1c000
	ds_read_b128 v[154:157], v153
	ds_read_b128 v[158:161], v153 offset:1024
	ds_read_b128 v[162:165], v153 offset:2048
	ds_read_b128 v[166:169], v153 offset:3072
	v_add_u32_e32 v153, s55, v148
	ds_read_b128 v[170:173], v153
	ds_read_b128 v[174:177], v153 offset:1024
	ds_read_b128 v[178:181], v153 offset:2048
	ds_read_b128 v[182:185], v153 offset:3072
	s_add_u32 s34, s34, 0x40000
	s_addc_u32 s35, s35, 0
	s_mov_b32 m0, s42
	v_lshl_add_u64 v[224:225], s[34:35], 0, v[136:137]
	ds_read_b128 v[186:189], v152 offset:32768
	ds_read_b128 v[190:193], v152 offset:33792
	ds_read_b128 v[194:197], v152 offset:34816
	ds_read_b128 v[198:201], v152 offset:35840
	ds_read_b128 v[202:205], v152 offset:36864
	ds_read_b128 v[206:209], v152 offset:37888
	ds_read_b128 v[210:213], v152 offset:38912
	ds_read_b128 v[214:217], v152 offset:39936
	global_load_lds_dwordx4 v[224:225], off
	v_lshl_add_u64 v[224:225], s[34:35], 0, v[132:133]
	s_mov_b32 m0, s43
	s_nop 0
	global_load_lds_dwordx4 v[224:225], off
	s_waitcnt vmcnt(8)
	s_waitcnt lgkmcnt(0)
	s_barrier
	s_waitcnt lgkmcnt(0)
	v_mfma_f32_16x16x32_bf16 v[126:129], v[154:157], v[186:189], v[126:129]
	v_mfma_f32_16x16x32_bf16 v[122:125], v[162:165], v[186:189], v[122:125]
	v_mfma_f32_16x16x32_bf16 v[110:113], v[154:157], v[194:197], v[110:113]
	v_mfma_f32_16x16x32_bf16 v[106:109], v[162:165], v[194:197], v[106:109]
	v_mfma_f32_16x16x32_bf16 v[94:97], v[154:157], v[202:205], v[94:97]
	v_mfma_f32_16x16x32_bf16 v[90:93], v[162:165], v[202:205], v[90:93]
	v_mfma_f32_16x16x32_bf16 v[78:81], v[154:157], v[210:213], v[78:81]
	v_mfma_f32_16x16x32_bf16 v[74:77], v[162:165], v[210:213], v[74:77]
	v_mfma_f32_16x16x32_bf16 v[126:129], v[158:161], v[190:193], v[126:129]
	v_mfma_f32_16x16x32_bf16 v[122:125], v[166:169], v[190:193], v[122:125]
	v_mfma_f32_16x16x32_bf16 v[110:113], v[158:161], v[198:201], v[110:113]
	v_mfma_f32_16x16x32_bf16 v[106:109], v[166:169], v[198:201], v[106:109]
	v_mfma_f32_16x16x32_bf16 v[94:97], v[158:161], v[206:209], v[94:97]
	v_mfma_f32_16x16x32_bf16 v[90:93], v[166:169], v[206:209], v[90:93]
	v_mfma_f32_16x16x32_bf16 v[78:81], v[158:161], v[214:217], v[78:81]
	v_mfma_f32_16x16x32_bf16 v[74:77], v[166:169], v[214:217], v[74:77]
	v_mfma_f32_16x16x32_bf16 v[118:121], v[170:173], v[186:189], v[118:121]
	v_mfma_f32_16x16x32_bf16 v[114:117], v[178:181], v[186:189], v[114:117]
	v_mfma_f32_16x16x32_bf16 v[102:105], v[170:173], v[194:197], v[102:105]
	v_mfma_f32_16x16x32_bf16 v[98:101], v[178:181], v[194:197], v[98:101]
	v_mfma_f32_16x16x32_bf16 v[86:89], v[170:173], v[202:205], v[86:89]
	v_mfma_f32_16x16x32_bf16 v[82:85], v[178:181], v[202:205], v[82:85]
	v_mfma_f32_16x16x32_bf16 v[70:73], v[170:173], v[210:213], v[70:73]
	v_mfma_f32_16x16x32_bf16 v[66:69], v[178:181], v[210:213], v[66:69]
	v_mfma_f32_16x16x32_bf16 v[118:121], v[174:177], v[190:193], v[118:121]
	v_mfma_f32_16x16x32_bf16 v[114:117], v[182:185], v[190:193], v[114:117]
	v_mfma_f32_16x16x32_bf16 v[102:105], v[174:177], v[198:201], v[102:105]
	v_mfma_f32_16x16x32_bf16 v[98:101], v[182:185], v[198:201], v[98:101]
	v_mfma_f32_16x16x32_bf16 v[86:89], v[174:177], v[206:209], v[86:89]
	v_mfma_f32_16x16x32_bf16 v[82:85], v[182:185], v[206:209], v[82:85]
	v_mfma_f32_16x16x32_bf16 v[70:73], v[174:177], v[214:217], v[70:73]
	v_mfma_f32_16x16x32_bf16 v[66:69], v[182:185], v[214:217], v[66:69]
	s_barrier
	s_add_i32 s34, s54, s38
	v_lshl_add_u64 v[146:147], v[146:147], 0, s[12:13]
	s_mov_b32 m0, s34
	ds_read_b128 v[186:189], v152 offset:49152
	ds_read_b128 v[190:193], v152 offset:50176
	ds_read_b128 v[194:197], v152 offset:51200
	ds_read_b128 v[198:201], v152 offset:52224
	ds_read_b128 v[202:205], v152 offset:53248
	ds_read_b128 v[206:209], v152 offset:54272
	ds_read_b128 v[210:213], v152 offset:55296
	ds_read_b128 v[214:217], v152 offset:56320
	global_load_lds_dwordx4 v[146:147], off
	s_add_i32 m0, s34, 0x2000
	s_add_u32 s30, s30, 0x40080
	v_lshl_add_u64 v[146:147], v[218:219], 0, s[12:13]
	s_addc_u32 s31, s31, 0
	s_add_i32 s34, s55, s38
	global_load_lds_dwordx4 v[146:147], off
	v_lshl_add_u64 v[146:147], s[30:31], 0, v[134:135]
	s_mov_b32 m0, s34
	s_nop 0
	global_load_lds_dwordx4 v[146:147], off
	v_lshl_add_u64 v[146:147], s[30:31], 0, v[130:131]
	s_add_i32 m0, s34, 0x2000
	s_nop 0
	global_load_lds_dwordx4 v[146:147], off
	v_lshl_add_u64 v[146:147], v[220:221], 0, s[12:13]
	s_mov_b32 m0, s45
	s_nop 0
	global_load_lds_dwordx4 v[146:147], off
	v_lshl_add_u64 v[146:147], v[222:223], 0, s[12:13]
	s_mov_b32 m0, s46
	s_nop 0
	global_load_lds_dwordx4 v[146:147], off
	s_waitcnt vmcnt(8)
	s_waitcnt lgkmcnt(0)
	s_barrier
	s_waitcnt lgkmcnt(0)
	v_mfma_f32_16x16x32_bf16 v[62:65], v[154:157], v[186:189], v[62:65]
	v_mfma_f32_16x16x32_bf16 v[58:61], v[162:165], v[186:189], v[58:61]
	v_mfma_f32_16x16x32_bf16 v[46:49], v[154:157], v[194:197], v[46:49]
	v_mfma_f32_16x16x32_bf16 v[42:45], v[162:165], v[194:197], v[42:45]
	v_mfma_f32_16x16x32_bf16 v[30:33], v[154:157], v[202:205], v[30:33]
	v_mfma_f32_16x16x32_bf16 v[26:29], v[162:165], v[202:205], v[26:29]
	v_mfma_f32_16x16x32_bf16 v[14:17], v[154:157], v[210:213], v[14:17]
	v_mfma_f32_16x16x32_bf16 v[10:13], v[162:165], v[210:213], v[10:13]
	v_mfma_f32_16x16x32_bf16 v[62:65], v[158:161], v[190:193], v[62:65]
	v_mfma_f32_16x16x32_bf16 v[58:61], v[166:169], v[190:193], v[58:61]
	v_mfma_f32_16x16x32_bf16 v[46:49], v[158:161], v[198:201], v[46:49]
	v_mfma_f32_16x16x32_bf16 v[42:45], v[166:169], v[198:201], v[42:45]
	v_mfma_f32_16x16x32_bf16 v[30:33], v[158:161], v[206:209], v[30:33]
	v_mfma_f32_16x16x32_bf16 v[26:29], v[166:169], v[206:209], v[26:29]
	v_mfma_f32_16x16x32_bf16 v[14:17], v[158:161], v[214:217], v[14:17]
	v_mfma_f32_16x16x32_bf16 v[10:13], v[166:169], v[214:217], v[10:13]
	v_mfma_f32_16x16x32_bf16 v[54:57], v[170:173], v[186:189], v[54:57]
	v_mfma_f32_16x16x32_bf16 v[50:53], v[178:181], v[186:189], v[50:53]
	v_mfma_f32_16x16x32_bf16 v[38:41], v[170:173], v[194:197], v[38:41]
	v_mfma_f32_16x16x32_bf16 v[34:37], v[178:181], v[194:197], v[34:37]
	v_mfma_f32_16x16x32_bf16 v[22:25], v[170:173], v[202:205], v[22:25]
	v_mfma_f32_16x16x32_bf16 v[18:21], v[178:181], v[202:205], v[18:21]
	v_mfma_f32_16x16x32_bf16 v[6:9], v[170:173], v[210:213], v[6:9]
	v_mfma_f32_16x16x32_bf16 v[2:5], v[178:181], v[210:213], v[2:5]
	v_mfma_f32_16x16x32_bf16 v[54:57], v[174:177], v[190:193], v[54:57]
	v_mfma_f32_16x16x32_bf16 v[50:53], v[182:185], v[190:193], v[50:53]
	v_mfma_f32_16x16x32_bf16 v[38:41], v[174:177], v[198:201], v[38:41]
	v_mfma_f32_16x16x32_bf16 v[34:37], v[182:185], v[198:201], v[34:37]
	v_mfma_f32_16x16x32_bf16 v[22:25], v[174:177], v[206:209], v[22:25]
	v_mfma_f32_16x16x32_bf16 v[18:21], v[182:185], v[206:209], v[18:21]
	v_mfma_f32_16x16x32_bf16 v[6:9], v[174:177], v[214:217], v[6:9]
	v_mfma_f32_16x16x32_bf16 v[2:5], v[182:185], v[214:217], v[2:5]
	s_barrier
	s_add_i32 s53, s53, 2
	s_add_u32 s28, s28, 0x100
	s_addc_u32 s29, s29, 0
	s_add_u32 s21, s21, 0x100
	s_addc_u32 s52, s52, 0
	s_cmp_gt_u32 s53, 13
	s_cbranch_scc0 .LBB0_86
	s_and_b64 vcc, exec, s[14:15]
	s_cbranch_vccz .LBB0_89
	s_barrier

.LBB0_138:
	ds_read_b128 v[152:155], v148
	ds_read_b128 v[156:159], v148 offset:1024
	ds_read_b128 v[160:163], v148 offset:2048
	ds_read_b128 v[164:167], v148 offset:3072
	ds_read_b128 v[168:171], v149
	ds_read_b128 v[172:175], v149 offset:1024
	ds_read_b128 v[176:179], v149 offset:2048
	ds_read_b128 v[180:183], v149 offset:3072
	s_add_u32 s30, s28, 0xfff50080
	s_addc_u32 s31, s29, -1
	s_cmp_eq_u32 s21, 40
	s_cselect_b32 s35, s5, s31
	s_cselect_b32 s34, s4, s30
	s_cselect_b32 s31, s27, s20
	s_cselect_b32 s30, s26, s10
	v_lshl_add_u64 v[216:217], s[28:29], 0, v[138:139]
	s_add_i32 m0, s42, 0xc000
	ds_read_b128 v[184:187], v150
	ds_read_b128 v[188:191], v150 offset:1024
	ds_read_b128 v[192:195], v150 offset:2048
	ds_read_b128 v[196:199], v150 offset:3072
	ds_read_b128 v[200:203], v150 offset:4096
	ds_read_b128 v[204:207], v150 offset:5120
	ds_read_b128 v[208:211], v150 offset:6144
	ds_read_b128 v[212:215], v150 offset:7168
	global_load_lds_dwordx4 v[216:217], off
	v_lshl_add_u64 v[216:217], s[28:29], 0, v[140:141]
	s_add_i32 m0, s42, 0xe000
	s_nop 0
	global_load_lds_dwordx4 v[216:217], off
	s_waitcnt vmcnt(8)
	s_waitcnt lgkmcnt(0)
	s_barrier
	s_waitcnt lgkmcnt(0)
	v_mfma_f32_16x16x32_bf16 v[126:129], v[152:155], v[184:187], v[126:129]
	v_mfma_f32_16x16x32_bf16 v[122:125], v[160:163], v[184:187], v[122:125]
	v_mfma_f32_16x16x32_bf16 v[118:121], v[152:155], v[192:195], v[118:121]
	v_mfma_f32_16x16x32_bf16 v[114:117], v[160:163], v[192:195], v[114:117]
	v_mfma_f32_16x16x32_bf16 v[102:105], v[152:155], v[200:203], v[102:105]
	v_mfma_f32_16x16x32_bf16 v[98:101], v[160:163], v[200:203], v[98:101]
	v_mfma_f32_16x16x32_bf16 v[86:89], v[152:155], v[208:211], v[86:89]
	v_mfma_f32_16x16x32_bf16 v[82:85], v[160:163], v[208:211], v[82:85]
	v_mfma_f32_16x16x32_bf16 v[126:129], v[156:159], v[188:191], v[126:129]
	v_mfma_f32_16x16x32_bf16 v[122:125], v[164:167], v[188:191], v[122:125]
	v_mfma_f32_16x16x32_bf16 v[118:121], v[156:159], v[196:199], v[118:121]
	v_mfma_f32_16x16x32_bf16 v[114:117], v[164:167], v[196:199], v[114:117]
	v_mfma_f32_16x16x32_bf16 v[102:105], v[156:159], v[204:207], v[102:105]
	v_mfma_f32_16x16x32_bf16 v[98:101], v[164:167], v[204:207], v[98:101]
	v_mfma_f32_16x16x32_bf16 v[86:89], v[156:159], v[212:215], v[86:89]
	v_mfma_f32_16x16x32_bf16 v[82:85], v[164:167], v[212:215], v[82:85]
	v_mfma_f32_16x16x32_bf16 v[110:113], v[168:171], v[184:187], v[110:113]
	v_mfma_f32_16x16x32_bf16 v[106:109], v[176:179], v[184:187], v[106:109]
	v_mfma_f32_16x16x32_bf16 v[94:97], v[168:171], v[192:195], v[94:97]
	v_mfma_f32_16x16x32_bf16 v[90:93], v[176:179], v[192:195], v[90:93]
	v_mfma_f32_16x16x32_bf16 v[78:81], v[168:171], v[200:203], v[78:81]
	v_mfma_f32_16x16x32_bf16 v[74:77], v[176:179], v[200:203], v[74:77]
	v_mfma_f32_16x16x32_bf16 v[70:73], v[168:171], v[208:211], v[70:73]
	v_mfma_f32_16x16x32_bf16 v[66:69], v[176:179], v[208:211], v[66:69]
	v_mfma_f32_16x16x32_bf16 v[110:113], v[172:175], v[188:191], v[110:113]
	v_mfma_f32_16x16x32_bf16 v[106:109], v[180:183], v[188:191], v[106:109]
	v_mfma_f32_16x16x32_bf16 v[94:97], v[172:175], v[196:199], v[94:97]
	v_mfma_f32_16x16x32_bf16 v[90:93], v[180:183], v[196:199], v[90:93]
	v_mfma_f32_16x16x32_bf16 v[78:81], v[172:175], v[204:207], v[78:81]
	v_mfma_f32_16x16x32_bf16 v[74:77], v[180:183], v[204:207], v[74:77]
	v_mfma_f32_16x16x32_bf16 v[70:73], v[172:175], v[212:215], v[70:73]
	v_mfma_f32_16x16x32_bf16 v[66:69], v[180:183], v[212:215], v[66:69]
	s_barrier
	s_add_i32 s60, s50, s41
	v_lshl_add_u64 v[216:217], s[30:31], 0, v[132:133]
	s_mov_b32 m0, s60
	ds_read_b128 v[184:187], v150 offset:16384
	ds_read_b128 v[188:191], v150 offset:17408
	ds_read_b128 v[192:195], v150 offset:18432
	ds_read_b128 v[196:199], v150 offset:19456
	ds_read_b128 v[200:203], v150 offset:20480
	ds_read_b128 v[204:207], v150 offset:21504
	ds_read_b128 v[208:211], v150 offset:22528
	ds_read_b128 v[212:215], v150 offset:23552
	global_load_lds_dwordx4 v[216:217], off
	s_add_i32 m0, s60, 0x2000
	s_add_u32 s60, s30, 0xb0000
	v_lshl_add_u64 v[218:219], s[30:31], 0, v[136:137]
	s_addc_u32 s61, s31, 0
	s_add_i32 s62, s51, s41
	global_load_lds_dwordx4 v[218:219], off
	v_lshl_add_u64 v[220:221], s[60:61], 0, v[132:133]
	s_mov_b32 m0, s62
	v_lshl_add_u64 v[222:223], s[34:35], 0, v[134:135]
	global_load_lds_dwordx4 v[220:221], off
	v_lshl_add_u64 v[220:221], s[60:61], 0, v[136:137]
	s_add_i32 m0, s62, 0x2000
	s_nop 0
	global_load_lds_dwordx4 v[220:221], off
	v_lshl_add_u64 v[220:221], s[34:35], 0, v[130:131]
	s_mov_b32 m0, s42
	s_nop 0
	global_load_lds_dwordx4 v[220:221], off
	s_mov_b32 m0, s43
	s_nop 0
	global_load_lds_dwordx4 v[222:223], off
	s_waitcnt vmcnt(8)
	s_waitcnt lgkmcnt(0)
	s_barrier
	s_waitcnt lgkmcnt(0)
	v_mfma_f32_16x16x32_bf16 v[62:65], v[152:155], v[184:187], v[62:65]
	v_mfma_f32_16x16x32_bf16 v[58:61], v[160:163], v[184:187], v[58:61]
	v_mfma_f32_16x16x32_bf16 v[54:57], v[152:155], v[192:195], v[54:57]
	v_mfma_f32_16x16x32_bf16 v[50:53], v[160:163], v[192:195], v[50:53]
	v_mfma_f32_16x16x32_bf16 v[38:41], v[152:155], v[200:203], v[38:41]
	v_mfma_f32_16x16x32_bf16 v[34:37], v[160:163], v[200:203], v[34:37]
	v_mfma_f32_16x16x32_bf16 v[22:25], v[152:155], v[208:211], v[22:25]
	v_mfma_f32_16x16x32_bf16 v[18:21], v[160:163], v[208:211], v[18:21]
	v_mfma_f32_16x16x32_bf16 v[62:65], v[156:159], v[188:191], v[62:65]
	v_mfma_f32_16x16x32_bf16 v[58:61], v[164:167], v[188:191], v[58:61]
	v_mfma_f32_16x16x32_bf16 v[54:57], v[156:159], v[196:199], v[54:57]
	v_mfma_f32_16x16x32_bf16 v[50:53], v[164:167], v[196:199], v[50:53]
	v_mfma_f32_16x16x32_bf16 v[38:41], v[156:159], v[204:207], v[38:41]
	v_mfma_f32_16x16x32_bf16 v[34:37], v[164:167], v[204:207], v[34:37]
	v_mfma_f32_16x16x32_bf16 v[22:25], v[156:159], v[212:215], v[22:25]
	v_mfma_f32_16x16x32_bf16 v[18:21], v[164:167], v[212:215], v[18:21]
	v_mfma_f32_16x16x32_bf16 v[46:49], v[168:171], v[184:187], v[46:49]
	v_mfma_f32_16x16x32_bf16 v[42:45], v[176:179], v[184:187], v[42:45]
	v_mfma_f32_16x16x32_bf16 v[30:33], v[168:171], v[192:195], v[30:33]
	v_mfma_f32_16x16x32_bf16 v[26:29], v[176:179], v[192:195], v[26:29]
	v_mfma_f32_16x16x32_bf16 v[14:17], v[168:171], v[200:203], v[14:17]
	v_mfma_f32_16x16x32_bf16 v[10:13], v[176:179], v[200:203], v[10:13]
	v_mfma_f32_16x16x32_bf16 v[6:9], v[168:171], v[208:211], v[6:9]
	v_mfma_f32_16x16x32_bf16 v[2:5], v[176:179], v[208:211], v[2:5]
	v_mfma_f32_16x16x32_bf16 v[46:49], v[172:175], v[188:191], v[46:49]
	v_mfma_f32_16x16x32_bf16 v[42:45], v[180:183], v[188:191], v[42:45]
	v_mfma_f32_16x16x32_bf16 v[30:33], v[172:175], v[196:199], v[30:33]
	v_mfma_f32_16x16x32_bf16 v[26:29], v[180:183], v[196:199], v[26:29]
	v_mfma_f32_16x16x32_bf16 v[14:17], v[172:175], v[204:207], v[14:17]
	v_mfma_f32_16x16x32_bf16 v[10:13], v[180:183], v[204:207], v[10:13]
	v_mfma_f32_16x16x32_bf16 v[6:9], v[172:175], v[212:215], v[6:9]
	v_mfma_f32_16x16x32_bf16 v[2:5], v[180:183], v[212:215], v[2:5]
	s_barrier
	s_add_i32 s60, 0, 0x18000
	v_add_u32_e32 v151, s60, v146
	s_add_i32 s61, 0, 0x1c000
	ds_read_b128 v[152:155], v151
	ds_read_b128 v[156:159], v151 offset:1024
	ds_read_b128 v[160:163], v151 offset:2048
	ds_read_b128 v[164:167], v151 offset:3072
	v_add_u32_e32 v151, s61, v146
	ds_read_b128 v[168:171], v151
	ds_read_b128 v[172:175], v151 offset:1024
	ds_read_b128 v[176:179], v151 offset:2048
	ds_read_b128 v[180:183], v151 offset:3072
	s_add_u32 s34, s34, 0xb0000
	s_addc_u32 s35, s35, 0
	s_mov_b32 m0, s44
	v_lshl_add_u64 v[224:225], s[34:35], 0, v[130:131]
	ds_read_b128 v[184:187], v150 offset:32768
	ds_read_b128 v[188:191], v150 offset:33792
	ds_read_b128 v[192:195], v150 offset:34816
	ds_read_b128 v[196:199], v150 offset:35840
	ds_read_b128 v[200:203], v150 offset:36864
	ds_read_b128 v[204:207], v150 offset:37888
	ds_read_b128 v[208:211], v150 offset:38912
	ds_read_b128 v[212:215], v150 offset:39936
	global_load_lds_dwordx4 v[224:225], off
	v_lshl_add_u64 v[224:225], s[34:35], 0, v[134:135]
	s_mov_b32 m0, s45
	s_nop 0
	global_load_lds_dwordx4 v[224:225], off
	s_waitcnt vmcnt(8)
	s_waitcnt lgkmcnt(0)
	s_barrier
	s_waitcnt lgkmcnt(0)
	v_mfma_f32_16x16x32_bf16 v[126:129], v[152:155], v[184:187], v[126:129]
	v_mfma_f32_16x16x32_bf16 v[122:125], v[160:163], v[184:187], v[122:125]
	v_mfma_f32_16x16x32_bf16 v[118:121], v[152:155], v[192:195], v[118:121]
	v_mfma_f32_16x16x32_bf16 v[114:117], v[160:163], v[192:195], v[114:117]
	v_mfma_f32_16x16x32_bf16 v[102:105], v[152:155], v[200:203], v[102:105]
	v_mfma_f32_16x16x32_bf16 v[98:101], v[160:163], v[200:203], v[98:101]
	v_mfma_f32_16x16x32_bf16 v[86:89], v[152:155], v[208:211], v[86:89]
	v_mfma_f32_16x16x32_bf16 v[82:85], v[160:163], v[208:211], v[82:85]
	v_mfma_f32_16x16x32_bf16 v[126:129], v[156:159], v[188:191], v[126:129]
	v_mfma_f32_16x16x32_bf16 v[122:125], v[164:167], v[188:191], v[122:125]
	v_mfma_f32_16x16x32_bf16 v[118:121], v[156:159], v[196:199], v[118:121]
	v_mfma_f32_16x16x32_bf16 v[114:117], v[164:167], v[196:199], v[114:117]
	v_mfma_f32_16x16x32_bf16 v[102:105], v[156:159], v[204:207], v[102:105]
	v_mfma_f32_16x16x32_bf16 v[98:101], v[164:167], v[204:207], v[98:101]
	v_mfma_f32_16x16x32_bf16 v[86:89], v[156:159], v[212:215], v[86:89]
	v_mfma_f32_16x16x32_bf16 v[82:85], v[164:167], v[212:215], v[82:85]
	v_mfma_f32_16x16x32_bf16 v[110:113], v[168:171], v[184:187], v[110:113]
	v_mfma_f32_16x16x32_bf16 v[106:109], v[176:179], v[184:187], v[106:109]
	v_mfma_f32_16x16x32_bf16 v[94:97], v[168:171], v[192:195], v[94:97]
	v_mfma_f32_16x16x32_bf16 v[90:93], v[176:179], v[192:195], v[90:93]
	v_mfma_f32_16x16x32_bf16 v[78:81], v[168:171], v[200:203], v[78:81]
	v_mfma_f32_16x16x32_bf16 v[74:77], v[176:179], v[200:203], v[74:77]
	v_mfma_f32_16x16x32_bf16 v[70:73], v[168:171], v[208:211], v[70:73]
	v_mfma_f32_16x16x32_bf16 v[66:69], v[176:179], v[208:211], v[66:69]
	v_mfma_f32_16x16x32_bf16 v[110:113], v[172:175], v[188:191], v[110:113]
	v_mfma_f32_16x16x32_bf16 v[106:109], v[180:183], v[188:191], v[106:109]
	v_mfma_f32_16x16x32_bf16 v[94:97], v[172:175], v[196:199], v[94:97]
	v_mfma_f32_16x16x32_bf16 v[90:93], v[180:183], v[196:199], v[90:93]
	v_mfma_f32_16x16x32_bf16 v[78:81], v[172:175], v[204:207], v[78:81]
	v_mfma_f32_16x16x32_bf16 v[74:77], v[180:183], v[204:207], v[74:77]
	v_mfma_f32_16x16x32_bf16 v[70:73], v[172:175], v[212:215], v[70:73]
	v_mfma_f32_16x16x32_bf16 v[66:69], v[180:183], v[212:215], v[66:69]
	s_barrier
	s_add_i32 s34, s60, s41
	v_lshl_add_u64 v[216:217], v[216:217], 0, s[12:13]
	s_mov_b32 m0, s34
	ds_read_b128 v[184:187], v150 offset:49152
	ds_read_b128 v[188:191], v150 offset:50176
	ds_read_b128 v[192:195], v150 offset:51200
	ds_read_b128 v[196:199], v150 offset:52224
	ds_read_b128 v[200:203], v150 offset:53248
	ds_read_b128 v[204:207], v150 offset:54272
	ds_read_b128 v[208:211], v150 offset:55296
	ds_read_b128 v[212:215], v150 offset:56320
	global_load_lds_dwordx4 v[216:217], off
	s_add_i32 m0, s34, 0x2000
	s_add_u32 s30, s30, 0xb0080
	v_lshl_add_u64 v[216:217], v[218:219], 0, s[12:13]
	s_addc_u32 s31, s31, 0
	s_add_i32 s34, s61, s41
	global_load_lds_dwordx4 v[216:217], off
	v_lshl_add_u64 v[216:217], s[30:31], 0, v[132:133]
	s_mov_b32 m0, s34
	s_nop 0
	global_load_lds_dwordx4 v[216:217], off
	v_lshl_add_u64 v[216:217], s[30:31], 0, v[136:137]
	s_add_i32 m0, s34, 0x2000
	s_nop 0
	global_load_lds_dwordx4 v[216:217], off
	v_lshl_add_u64 v[216:217], v[220:221], 0, s[12:13]
	s_mov_b32 m0, s47
	s_nop 0
	global_load_lds_dwordx4 v[216:217], off
	v_lshl_add_u64 v[216:217], v[222:223], 0, s[12:13]
	s_mov_b32 m0, s48
	s_nop 0
	global_load_lds_dwordx4 v[216:217], off
	s_waitcnt vmcnt(8)
	s_waitcnt lgkmcnt(0)
	s_barrier
	s_waitcnt lgkmcnt(0)
	v_mfma_f32_16x16x32_bf16 v[62:65], v[152:155], v[184:187], v[62:65]
	v_mfma_f32_16x16x32_bf16 v[58:61], v[160:163], v[184:187], v[58:61]
	v_mfma_f32_16x16x32_bf16 v[54:57], v[152:155], v[192:195], v[54:57]
	v_mfma_f32_16x16x32_bf16 v[50:53], v[160:163], v[192:195], v[50:53]
	v_mfma_f32_16x16x32_bf16 v[38:41], v[152:155], v[200:203], v[38:41]
	v_mfma_f32_16x16x32_bf16 v[34:37], v[160:163], v[200:203], v[34:37]
	v_mfma_f32_16x16x32_bf16 v[22:25], v[152:155], v[208:211], v[22:25]
	v_mfma_f32_16x16x32_bf16 v[18:21], v[160:163], v[208:211], v[18:21]
	v_mfma_f32_16x16x32_bf16 v[62:65], v[156:159], v[188:191], v[62:65]
	v_mfma_f32_16x16x32_bf16 v[58:61], v[164:167], v[188:191], v[58:61]
	v_mfma_f32_16x16x32_bf16 v[54:57], v[156:159], v[196:199], v[54:57]
	v_mfma_f32_16x16x32_bf16 v[50:53], v[164:167], v[196:199], v[50:53]
	v_mfma_f32_16x16x32_bf16 v[38:41], v[156:159], v[204:207], v[38:41]
	v_mfma_f32_16x16x32_bf16 v[34:37], v[164:167], v[204:207], v[34:37]
	v_mfma_f32_16x16x32_bf16 v[22:25], v[156:159], v[212:215], v[22:25]
	v_mfma_f32_16x16x32_bf16 v[18:21], v[164:167], v[212:215], v[18:21]
	v_mfma_f32_16x16x32_bf16 v[46:49], v[168:171], v[184:187], v[46:49]
	v_mfma_f32_16x16x32_bf16 v[42:45], v[176:179], v[184:187], v[42:45]
	v_mfma_f32_16x16x32_bf16 v[30:33], v[168:171], v[192:195], v[30:33]
	v_mfma_f32_16x16x32_bf16 v[26:29], v[176:179], v[192:195], v[26:29]
	v_mfma_f32_16x16x32_bf16 v[14:17], v[168:171], v[200:203], v[14:17]
	v_mfma_f32_16x16x32_bf16 v[10:13], v[176:179], v[200:203], v[10:13]
	v_mfma_f32_16x16x32_bf16 v[6:9], v[168:171], v[208:211], v[6:9]
	v_mfma_f32_16x16x32_bf16 v[2:5], v[176:179], v[208:211], v[2:5]
	v_mfma_f32_16x16x32_bf16 v[46:49], v[172:175], v[188:191], v[46:49]
	v_mfma_f32_16x16x32_bf16 v[42:45], v[180:183], v[188:191], v[42:45]
	v_mfma_f32_16x16x32_bf16 v[30:33], v[172:175], v[196:199], v[30:33]
	v_mfma_f32_16x16x32_bf16 v[26:29], v[180:183], v[196:199], v[26:29]
	v_mfma_f32_16x16x32_bf16 v[14:17], v[172:175], v[204:207], v[14:17]
	v_mfma_f32_16x16x32_bf16 v[10:13], v[180:183], v[204:207], v[10:13]
	v_mfma_f32_16x16x32_bf16 v[6:9], v[172:175], v[212:215], v[6:9]
	v_mfma_f32_16x16x32_bf16 v[2:5], v[180:183], v[212:215], v[2:5]
	s_barrier
	s_add_i32 s21, s21, 2
	s_add_u32 s28, s28, 0x100
	s_addc_u32 s29, s29, 0
	s_add_u32 s10, s10, 0x100
	s_addc_u32 s20, s20, 0
	s_cmp_gt_u32 s21, 41
	s_cbranch_scc0 .LBB0_138
	s_and_b64 vcc, exec, s[14:15]
	s_cbranch_vccz .LBB0_141
	s_barrier

.LBB0_209:
	ds_read_b128 v[130:133], v197
	ds_read_b128 v[134:137], v197 offset:1024
	s_waitcnt vmcnt(0)
	ds_read_b128 v[138:141], v197 offset:2048
	ds_read_b128 v[142:145], v197 offset:3072
	ds_read_b128 v[146:149], v198
	ds_read_b128 v[150:153], v198 offset:1024
	ds_read_b128 v[176:179], v198 offset:2048
	ds_read_b128 v[180:183], v198 offset:3072
	s_add_u32 s48, s46, 0xfffc0080
	s_addc_u32 s49, s47, -1
	s_cmp_eq_u32 s73, 12
	s_cselect_b32 s51, s7, s49
	s_cselect_b32 s50, s10, s48
	s_cselect_b32 s49, s20, s39
	s_cselect_b32 s48, s21, s37
	s_waitcnt lgkmcnt(0)
	v_lshl_add_u64 v[192:193], s[46:47], 0, v[168:169]
	s_add_i32 m0, s45, 0xc000
	ds_read_b128 v[184:187], v199
	ds_read_b128 v[188:191], v199 offset:1024
	ds_read_b128 v[202:205], v199 offset:2048
	ds_read_b128 v[206:209], v199 offset:3072
	ds_read_b128 v[210:213], v199 offset:4096
	ds_read_b128 v[214:217], v199 offset:5120
	ds_read_b128 v[218:221], v199 offset:6144
	ds_read_b128 v[222:225], v199 offset:7168
	global_load_lds_dwordx4 v[192:193], off
	v_lshl_add_u64 v[192:193], s[46:47], 0, v[170:171]
	s_add_i32 m0, s45, 0xe000
	s_nop 0
	global_load_lds_dwordx4 v[192:193], off
	s_waitcnt vmcnt(8)
	s_waitcnt lgkmcnt(0)
	s_barrier
	s_waitcnt lgkmcnt(0)
	v_mfma_f32_16x16x32_bf16 v[126:129], v[130:133], v[184:187], v[126:129]
	v_mfma_f32_16x16x32_bf16 v[122:125], v[138:141], v[184:187], v[122:125]
	v_mfma_f32_16x16x32_bf16 v[110:113], v[130:133], v[202:205], v[110:113]
	v_mfma_f32_16x16x32_bf16 v[106:109], v[138:141], v[202:205], v[106:109]
	v_mfma_f32_16x16x32_bf16 v[94:97], v[130:133], v[210:213], v[94:97]
	v_mfma_f32_16x16x32_bf16 v[90:93], v[138:141], v[210:213], v[90:93]
	v_mfma_f32_16x16x32_bf16 v[78:81], v[130:133], v[218:221], v[78:81]
	v_mfma_f32_16x16x32_bf16 v[74:77], v[138:141], v[218:221], v[74:77]
	v_mfma_f32_16x16x32_bf16 v[126:129], v[134:137], v[188:191], v[126:129]
	v_mfma_f32_16x16x32_bf16 v[122:125], v[142:145], v[188:191], v[122:125]
	v_mfma_f32_16x16x32_bf16 v[110:113], v[134:137], v[206:209], v[110:113]
	v_mfma_f32_16x16x32_bf16 v[106:109], v[142:145], v[206:209], v[106:109]
	v_mfma_f32_16x16x32_bf16 v[94:97], v[134:137], v[214:217], v[94:97]
	v_mfma_f32_16x16x32_bf16 v[90:93], v[142:145], v[214:217], v[90:93]
	v_mfma_f32_16x16x32_bf16 v[78:81], v[134:137], v[222:225], v[78:81]
	v_mfma_f32_16x16x32_bf16 v[74:77], v[142:145], v[222:225], v[74:77]
	v_mfma_f32_16x16x32_bf16 v[118:121], v[146:149], v[184:187], v[118:121]
	v_mfma_f32_16x16x32_bf16 v[114:117], v[176:179], v[184:187], v[114:117]
	v_mfma_f32_16x16x32_bf16 v[102:105], v[146:149], v[202:205], v[102:105]
	v_mfma_f32_16x16x32_bf16 v[98:101], v[176:179], v[202:205], v[98:101]
	v_mfma_f32_16x16x32_bf16 v[86:89], v[146:149], v[210:213], v[86:89]
	v_mfma_f32_16x16x32_bf16 v[82:85], v[176:179], v[210:213], v[82:85]
	v_mfma_f32_16x16x32_bf16 v[70:73], v[146:149], v[218:221], v[70:73]
	v_mfma_f32_16x16x32_bf16 v[66:69], v[176:179], v[218:221], v[66:69]
	v_mfma_f32_16x16x32_bf16 v[118:121], v[150:153], v[188:191], v[118:121]
	v_mfma_f32_16x16x32_bf16 v[114:117], v[180:183], v[188:191], v[114:117]
	v_mfma_f32_16x16x32_bf16 v[102:105], v[150:153], v[206:209], v[102:105]
	v_mfma_f32_16x16x32_bf16 v[98:101], v[180:183], v[206:209], v[98:101]
	v_mfma_f32_16x16x32_bf16 v[86:89], v[150:153], v[214:217], v[86:89]
	v_mfma_f32_16x16x32_bf16 v[82:85], v[180:183], v[214:217], v[82:85]
	v_mfma_f32_16x16x32_bf16 v[70:73], v[150:153], v[222:225], v[70:73]
	v_mfma_f32_16x16x32_bf16 v[66:69], v[180:183], v[222:225], v[66:69]
	s_barrier
	s_add_i32 s74, s66, s56
	v_lshl_add_u64 v[192:193], s[48:49], 0, v[156:157]
	s_mov_b32 m0, s74
	ds_read_b128 v[184:187], v199 offset:16384
	ds_read_b128 v[188:191], v199 offset:17408
	ds_read_b128 v[202:205], v199 offset:18432
	ds_read_b128 v[206:209], v199 offset:19456
	ds_read_b128 v[210:213], v199 offset:20480
	ds_read_b128 v[214:217], v199 offset:21504
	ds_read_b128 v[218:221], v199 offset:22528
	ds_read_b128 v[222:225], v199 offset:23552
	global_load_lds_dwordx4 v[192:193], off
	s_add_i32 m0, s74, 0x2000
	s_add_u32 s74, s48, 0x40000
	v_lshl_add_u64 v[226:227], s[48:49], 0, v[160:161]
	s_addc_u32 s75, s49, 0
	s_add_i32 s76, s67, s56
	global_load_lds_dwordx4 v[226:227], off
	v_lshl_add_u64 v[228:229], s[74:75], 0, v[156:157]
	s_mov_b32 m0, s76
	v_lshl_add_u64 v[230:231], s[50:51], 0, v[158:159]
	global_load_lds_dwordx4 v[228:229], off
	v_lshl_add_u64 v[228:229], s[74:75], 0, v[160:161]
	s_add_i32 m0, s76, 0x2000
	s_nop 0
	global_load_lds_dwordx4 v[228:229], off
	v_lshl_add_u64 v[228:229], s[50:51], 0, v[154:155]
	s_mov_b32 m0, s45
	s_nop 0
	global_load_lds_dwordx4 v[228:229], off
	s_mov_b32 m0, s57
	s_nop 0
	global_load_lds_dwordx4 v[230:231], off
	s_waitcnt vmcnt(8)
	s_waitcnt lgkmcnt(0)
	s_barrier
	s_waitcnt lgkmcnt(0)
	v_mfma_f32_16x16x32_bf16 v[62:65], v[130:133], v[184:187], v[62:65]
	v_mfma_f32_16x16x32_bf16 v[58:61], v[138:141], v[184:187], v[58:61]
	v_mfma_f32_16x16x32_bf16 v[46:49], v[130:133], v[202:205], v[46:49]
	v_mfma_f32_16x16x32_bf16 v[42:45], v[138:141], v[202:205], v[42:45]
	v_mfma_f32_16x16x32_bf16 v[30:33], v[130:133], v[210:213], v[30:33]
	v_mfma_f32_16x16x32_bf16 v[26:29], v[138:141], v[210:213], v[26:29]
	v_mfma_f32_16x16x32_bf16 v[14:17], v[130:133], v[218:221], v[14:17]
	v_mfma_f32_16x16x32_bf16 v[10:13], v[138:141], v[218:221], v[10:13]
	v_mfma_f32_16x16x32_bf16 v[62:65], v[134:137], v[188:191], v[62:65]
	v_mfma_f32_16x16x32_bf16 v[58:61], v[142:145], v[188:191], v[58:61]
	v_mfma_f32_16x16x32_bf16 v[46:49], v[134:137], v[206:209], v[46:49]
	v_mfma_f32_16x16x32_bf16 v[42:45], v[142:145], v[206:209], v[42:45]
	v_mfma_f32_16x16x32_bf16 v[30:33], v[134:137], v[214:217], v[30:33]
	v_mfma_f32_16x16x32_bf16 v[26:29], v[142:145], v[214:217], v[26:29]
	v_mfma_f32_16x16x32_bf16 v[14:17], v[134:137], v[222:225], v[14:17]
	v_mfma_f32_16x16x32_bf16 v[10:13], v[142:145], v[222:225], v[10:13]
	v_mfma_f32_16x16x32_bf16 v[54:57], v[146:149], v[184:187], v[54:57]
	v_mfma_f32_16x16x32_bf16 v[50:53], v[176:179], v[184:187], v[50:53]
	v_mfma_f32_16x16x32_bf16 v[38:41], v[146:149], v[202:205], v[38:41]
	v_mfma_f32_16x16x32_bf16 v[34:37], v[176:179], v[202:205], v[34:37]
	v_mfma_f32_16x16x32_bf16 v[22:25], v[146:149], v[210:213], v[22:25]
	v_mfma_f32_16x16x32_bf16 v[18:21], v[176:179], v[210:213], v[18:21]
	v_mfma_f32_16x16x32_bf16 v[6:9], v[146:149], v[218:221], v[6:9]
	v_mfma_f32_16x16x32_bf16 v[2:5], v[176:179], v[218:221], v[2:5]
	v_mfma_f32_16x16x32_bf16 v[54:57], v[150:153], v[188:191], v[54:57]
	v_mfma_f32_16x16x32_bf16 v[50:53], v[180:183], v[188:191], v[50:53]
	v_mfma_f32_16x16x32_bf16 v[38:41], v[150:153], v[206:209], v[38:41]
	v_mfma_f32_16x16x32_bf16 v[34:37], v[180:183], v[206:209], v[34:37]
	v_mfma_f32_16x16x32_bf16 v[22:25], v[150:153], v[214:217], v[22:25]
	v_mfma_f32_16x16x32_bf16 v[18:21], v[180:183], v[214:217], v[18:21]
	v_mfma_f32_16x16x32_bf16 v[6:9], v[150:153], v[222:225], v[6:9]
	v_mfma_f32_16x16x32_bf16 v[2:5], v[180:183], v[222:225], v[2:5]
	s_barrier
	s_add_i32 s74, 0, 0x18000
	s_add_i32 s75, 0, 0x1c000
	v_add_u32_e32 v142, s74, v194
	v_add_u32_e32 v162, s75, v194
	ds_read_b128 v[130:133], v142
	ds_read_b128 v[134:137], v142 offset:1024
	ds_read_b128 v[138:141], v142 offset:2048
	ds_read_b128 v[142:145], v142 offset:3072
	ds_read_b128 v[146:149], v162
	ds_read_b128 v[150:153], v162 offset:1024
	ds_read_b128 v[176:179], v162 offset:2048
	ds_read_b128 v[180:183], v162 offset:3072
	s_add_u32 s50, s50, 0x40000
	s_addc_u32 s51, s51, 0
	s_mov_b32 m0, s58
	v_lshl_add_u64 v[232:233], s[50:51], 0, v[154:155]
	ds_read_b128 v[184:187], v199 offset:32768
	ds_read_b128 v[188:191], v199 offset:33792
	ds_read_b128 v[202:205], v199 offset:34816
	ds_read_b128 v[206:209], v199 offset:35840
	ds_read_b128 v[210:213], v199 offset:36864
	ds_read_b128 v[214:217], v199 offset:37888
	ds_read_b128 v[218:221], v199 offset:38912
	ds_read_b128 v[222:225], v199 offset:39936
	global_load_lds_dwordx4 v[232:233], off
	v_lshl_add_u64 v[232:233], s[50:51], 0, v[158:159]
	s_mov_b32 m0, s59
	s_nop 0
	global_load_lds_dwordx4 v[232:233], off
	s_waitcnt vmcnt(8)
	s_waitcnt lgkmcnt(0)
	s_barrier
	s_waitcnt lgkmcnt(0)
	v_mfma_f32_16x16x32_bf16 v[126:129], v[130:133], v[184:187], v[126:129]
	v_mfma_f32_16x16x32_bf16 v[122:125], v[138:141], v[184:187], v[122:125]
	v_mfma_f32_16x16x32_bf16 v[110:113], v[130:133], v[202:205], v[110:113]
	v_mfma_f32_16x16x32_bf16 v[106:109], v[138:141], v[202:205], v[106:109]
	v_mfma_f32_16x16x32_bf16 v[94:97], v[130:133], v[210:213], v[94:97]
	v_mfma_f32_16x16x32_bf16 v[90:93], v[138:141], v[210:213], v[90:93]
	v_mfma_f32_16x16x32_bf16 v[78:81], v[130:133], v[218:221], v[78:81]
	v_mfma_f32_16x16x32_bf16 v[74:77], v[138:141], v[218:221], v[74:77]
	v_mfma_f32_16x16x32_bf16 v[126:129], v[134:137], v[188:191], v[126:129]
	v_mfma_f32_16x16x32_bf16 v[122:125], v[142:145], v[188:191], v[122:125]
	v_mfma_f32_16x16x32_bf16 v[110:113], v[134:137], v[206:209], v[110:113]
	v_mfma_f32_16x16x32_bf16 v[106:109], v[142:145], v[206:209], v[106:109]
	v_mfma_f32_16x16x32_bf16 v[94:97], v[134:137], v[214:217], v[94:97]
	v_mfma_f32_16x16x32_bf16 v[90:93], v[142:145], v[214:217], v[90:93]
	v_mfma_f32_16x16x32_bf16 v[78:81], v[134:137], v[222:225], v[78:81]
	v_mfma_f32_16x16x32_bf16 v[74:77], v[142:145], v[222:225], v[74:77]
	v_mfma_f32_16x16x32_bf16 v[118:121], v[146:149], v[184:187], v[118:121]
	v_mfma_f32_16x16x32_bf16 v[114:117], v[176:179], v[184:187], v[114:117]
	v_mfma_f32_16x16x32_bf16 v[102:105], v[146:149], v[202:205], v[102:105]
	v_mfma_f32_16x16x32_bf16 v[98:101], v[176:179], v[202:205], v[98:101]
	v_mfma_f32_16x16x32_bf16 v[86:89], v[146:149], v[210:213], v[86:89]
	v_mfma_f32_16x16x32_bf16 v[82:85], v[176:179], v[210:213], v[82:85]
	v_mfma_f32_16x16x32_bf16 v[70:73], v[146:149], v[218:221], v[70:73]
	v_mfma_f32_16x16x32_bf16 v[66:69], v[176:179], v[218:221], v[66:69]
	v_mfma_f32_16x16x32_bf16 v[118:121], v[150:153], v[188:191], v[118:121]
	v_mfma_f32_16x16x32_bf16 v[114:117], v[180:183], v[188:191], v[114:117]
	v_mfma_f32_16x16x32_bf16 v[102:105], v[150:153], v[206:209], v[102:105]
	v_mfma_f32_16x16x32_bf16 v[98:101], v[180:183], v[206:209], v[98:101]
	v_mfma_f32_16x16x32_bf16 v[86:89], v[150:153], v[214:217], v[86:89]
	v_mfma_f32_16x16x32_bf16 v[82:85], v[180:183], v[214:217], v[82:85]
	v_mfma_f32_16x16x32_bf16 v[70:73], v[150:153], v[222:225], v[70:73]
	v_mfma_f32_16x16x32_bf16 v[66:69], v[180:183], v[222:225], v[66:69]
	s_barrier
	s_add_i32 s50, s74, s56
	v_lshl_add_u64 v[192:193], v[192:193], 0, s[18:19]
	s_mov_b32 m0, s50
	ds_read_b128 v[184:187], v199 offset:49152
	ds_read_b128 v[188:191], v199 offset:50176
	ds_read_b128 v[202:205], v199 offset:51200
	ds_read_b128 v[206:209], v199 offset:52224
	ds_read_b128 v[210:213], v199 offset:53248
	ds_read_b128 v[214:217], v199 offset:54272
	ds_read_b128 v[218:221], v199 offset:55296
	ds_read_b128 v[222:225], v199 offset:56320
	global_load_lds_dwordx4 v[192:193], off
	s_add_i32 m0, s50, 0x2000
	s_add_u32 s48, s48, 0x40080
	v_lshl_add_u64 v[192:193], v[226:227], 0, s[18:19]
	s_addc_u32 s49, s49, 0
	s_add_i32 s50, s75, s56
	global_load_lds_dwordx4 v[192:193], off
	v_lshl_add_u64 v[192:193], s[48:49], 0, v[156:157]
	s_mov_b32 m0, s50
	s_nop 0
	global_load_lds_dwordx4 v[192:193], off
	v_lshl_add_u64 v[192:193], s[48:49], 0, v[160:161]
	s_add_i32 m0, s50, 0x2000
	s_nop 0
	global_load_lds_dwordx4 v[192:193], off
	v_lshl_add_u64 v[192:193], v[228:229], 0, s[18:19]
	s_mov_b32 m0, s61
	s_nop 0
	global_load_lds_dwordx4 v[192:193], off
	v_lshl_add_u64 v[192:193], v[230:231], 0, s[18:19]
	s_mov_b32 m0, s62
	s_nop 0
	global_load_lds_dwordx4 v[192:193], off
	s_waitcnt vmcnt(8)
	s_waitcnt lgkmcnt(0)
	s_barrier
	s_waitcnt lgkmcnt(0)
	v_mfma_f32_16x16x32_bf16 v[62:65], v[130:133], v[184:187], v[62:65]
	v_mfma_f32_16x16x32_bf16 v[58:61], v[138:141], v[184:187], v[58:61]
	v_mfma_f32_16x16x32_bf16 v[46:49], v[130:133], v[202:205], v[46:49]
	v_mfma_f32_16x16x32_bf16 v[42:45], v[138:141], v[202:205], v[42:45]
	v_mfma_f32_16x16x32_bf16 v[30:33], v[130:133], v[210:213], v[30:33]
	v_mfma_f32_16x16x32_bf16 v[26:29], v[138:141], v[210:213], v[26:29]
	v_mfma_f32_16x16x32_bf16 v[14:17], v[130:133], v[218:221], v[14:17]
	v_mfma_f32_16x16x32_bf16 v[10:13], v[138:141], v[218:221], v[10:13]
	v_mfma_f32_16x16x32_bf16 v[62:65], v[134:137], v[188:191], v[62:65]
	v_mfma_f32_16x16x32_bf16 v[58:61], v[142:145], v[188:191], v[58:61]
	v_mfma_f32_16x16x32_bf16 v[46:49], v[134:137], v[206:209], v[46:49]
	v_mfma_f32_16x16x32_bf16 v[42:45], v[142:145], v[206:209], v[42:45]
	v_mfma_f32_16x16x32_bf16 v[30:33], v[134:137], v[214:217], v[30:33]
	v_mfma_f32_16x16x32_bf16 v[26:29], v[142:145], v[214:217], v[26:29]
	v_mfma_f32_16x16x32_bf16 v[14:17], v[134:137], v[222:225], v[14:17]
	v_mfma_f32_16x16x32_bf16 v[10:13], v[142:145], v[222:225], v[10:13]
	v_mfma_f32_16x16x32_bf16 v[54:57], v[146:149], v[184:187], v[54:57]
	v_mfma_f32_16x16x32_bf16 v[50:53], v[176:179], v[184:187], v[50:53]
	v_mfma_f32_16x16x32_bf16 v[38:41], v[146:149], v[202:205], v[38:41]
	v_mfma_f32_16x16x32_bf16 v[34:37], v[176:179], v[202:205], v[34:37]
	v_mfma_f32_16x16x32_bf16 v[22:25], v[146:149], v[210:213], v[22:25]
	v_mfma_f32_16x16x32_bf16 v[18:21], v[176:179], v[210:213], v[18:21]
	v_mfma_f32_16x16x32_bf16 v[6:9], v[146:149], v[218:221], v[6:9]
	v_mfma_f32_16x16x32_bf16 v[2:5], v[176:179], v[218:221], v[2:5]
	v_mfma_f32_16x16x32_bf16 v[54:57], v[150:153], v[188:191], v[54:57]
	v_mfma_f32_16x16x32_bf16 v[50:53], v[180:183], v[188:191], v[50:53]
	v_mfma_f32_16x16x32_bf16 v[38:41], v[150:153], v[206:209], v[38:41]
	v_mfma_f32_16x16x32_bf16 v[34:37], v[180:183], v[206:209], v[34:37]
	v_mfma_f32_16x16x32_bf16 v[22:25], v[150:153], v[214:217], v[22:25]
	v_mfma_f32_16x16x32_bf16 v[18:21], v[180:183], v[214:217], v[18:21]
	v_mfma_f32_16x16x32_bf16 v[6:9], v[150:153], v[222:225], v[6:9]
	v_mfma_f32_16x16x32_bf16 v[2:5], v[180:183], v[222:225], v[2:5]
	s_barrier
	s_add_i32 s73, s73, 2
	s_add_u32 s46, s46, 0x100
	s_addc_u32 s47, s47, 0
	s_add_u32 s37, s37, 0x100
	s_addc_u32 s39, s39, 0
	s_cmp_gt_u32 s73, 13
	s_cbranch_scc0 .LBB0_209
	s_and_b64 vcc, exec, s[22:23]
	s_cbranch_vccz .LBB0_212
	s_barrier

.LBB0_502:
	ds_read_b128 v[146:149], v164
	ds_read_b128 v[168:171], v164 offset:1024
	ds_read_b128 v[172:175], v164 offset:2048
	ds_read_b128 v[176:179], v164 offset:3072
	ds_read_b128 v[180:183], v165
	ds_read_b128 v[184:187], v165 offset:1024
	ds_read_b128 v[188:191], v165 offset:2048
	ds_read_b128 v[192:195], v165 offset:3072
	s_add_i32 s60, s21, 2
	s_add_u32 s36, s34, 0xffeb0080
	s_addc_u32 s37, s35, -1
	s_cmp_eq_u32 s52, s21
	s_cselect_b32 s37, s5, s37
	s_cselect_b32 s36, s4, s36
	s_cselect_b32 s63, s31, s20
	s_cselect_b32 s62, s30, s10
	v_lshl_add_u64 v[228:229], s[34:35], 0, v[138:139]
	s_add_i32 m0, s44, 0xc000
	ds_read_b128 v[196:199], v166
	ds_read_b128 v[200:203], v166 offset:1024
	ds_read_b128 v[204:207], v166 offset:2048
	ds_read_b128 v[208:211], v166 offset:3072
	ds_read_b128 v[212:215], v166 offset:4096
	ds_read_b128 v[216:219], v166 offset:5120
	ds_read_b128 v[220:223], v166 offset:6144
	ds_read_b128 v[224:227], v166 offset:7168
	global_load_lds_dwordx4 v[228:229], off
	v_lshl_add_u64 v[228:229], s[34:35], 0, v[140:141]
	s_add_i32 m0, s44, 0xe000
	s_nop 0
	global_load_lds_dwordx4 v[228:229], off
	s_waitcnt vmcnt(8)
	s_waitcnt lgkmcnt(0)
	s_barrier
	s_waitcnt lgkmcnt(0)
	v_mfma_f32_16x16x32_bf16 v[126:129], v[146:149], v[196:199], v[126:129]
	v_mfma_f32_16x16x32_bf16 v[122:125], v[172:175], v[196:199], v[122:125]
	v_mfma_f32_16x16x32_bf16 v[110:113], v[146:149], v[204:207], v[110:113]
	v_mfma_f32_16x16x32_bf16 v[106:109], v[172:175], v[204:207], v[106:109]
	v_mfma_f32_16x16x32_bf16 v[94:97], v[146:149], v[212:215], v[94:97]
	v_mfma_f32_16x16x32_bf16 v[90:93], v[172:175], v[212:215], v[90:93]
	v_mfma_f32_16x16x32_bf16 v[78:81], v[146:149], v[220:223], v[78:81]
	v_mfma_f32_16x16x32_bf16 v[74:77], v[172:175], v[220:223], v[74:77]
	v_mfma_f32_16x16x32_bf16 v[126:129], v[168:171], v[200:203], v[126:129]
	v_mfma_f32_16x16x32_bf16 v[122:125], v[176:179], v[200:203], v[122:125]
	v_mfma_f32_16x16x32_bf16 v[110:113], v[168:171], v[208:211], v[110:113]
	v_mfma_f32_16x16x32_bf16 v[106:109], v[176:179], v[208:211], v[106:109]
	v_mfma_f32_16x16x32_bf16 v[94:97], v[168:171], v[216:219], v[94:97]
	v_mfma_f32_16x16x32_bf16 v[90:93], v[176:179], v[216:219], v[90:93]
	v_mfma_f32_16x16x32_bf16 v[78:81], v[168:171], v[224:227], v[78:81]
	v_mfma_f32_16x16x32_bf16 v[74:77], v[176:179], v[224:227], v[74:77]
	v_mfma_f32_16x16x32_bf16 v[118:121], v[180:183], v[196:199], v[118:121]
	v_mfma_f32_16x16x32_bf16 v[114:117], v[188:191], v[196:199], v[114:117]
	v_mfma_f32_16x16x32_bf16 v[102:105], v[180:183], v[204:207], v[102:105]
	v_mfma_f32_16x16x32_bf16 v[98:101], v[188:191], v[204:207], v[98:101]
	v_mfma_f32_16x16x32_bf16 v[86:89], v[180:183], v[212:215], v[86:89]
	v_mfma_f32_16x16x32_bf16 v[82:85], v[188:191], v[212:215], v[82:85]
	v_mfma_f32_16x16x32_bf16 v[70:73], v[180:183], v[220:223], v[70:73]
	v_mfma_f32_16x16x32_bf16 v[66:69], v[188:191], v[220:223], v[66:69]
	v_mfma_f32_16x16x32_bf16 v[118:121], v[184:187], v[200:203], v[118:121]
	v_mfma_f32_16x16x32_bf16 v[114:117], v[192:195], v[200:203], v[114:117]
	v_mfma_f32_16x16x32_bf16 v[102:105], v[184:187], v[208:211], v[102:105]
	v_mfma_f32_16x16x32_bf16 v[98:101], v[192:195], v[208:211], v[98:101]
	v_mfma_f32_16x16x32_bf16 v[86:89], v[184:187], v[216:219], v[86:89]
	v_mfma_f32_16x16x32_bf16 v[82:85], v[192:195], v[216:219], v[82:85]
	v_mfma_f32_16x16x32_bf16 v[70:73], v[184:187], v[224:227], v[70:73]
	v_mfma_f32_16x16x32_bf16 v[66:69], v[192:195], v[224:227], v[66:69]
	s_barrier
	s_add_i32 s21, s54, s43
	v_lshl_add_u64 v[228:229], s[62:63], 0, v[132:133]
	s_mov_b32 m0, s21
	ds_read_b128 v[196:199], v166 offset:16384
	ds_read_b128 v[200:203], v166 offset:17408
	ds_read_b128 v[204:207], v166 offset:18432
	ds_read_b128 v[208:211], v166 offset:19456
	ds_read_b128 v[212:215], v166 offset:20480
	ds_read_b128 v[216:219], v166 offset:21504
	ds_read_b128 v[220:223], v166 offset:22528
	ds_read_b128 v[224:227], v166 offset:23552
	global_load_lds_dwordx4 v[228:229], off
	s_add_i32 m0, s21, 0x2000
	v_lshl_add_u64 v[230:231], s[62:63], 0, v[136:137]
	s_add_u32 s62, s62, s16
	s_addc_u32 s63, s63, s17
	s_add_i32 s21, s55, s43
	global_load_lds_dwordx4 v[230:231], off
	v_lshl_add_u64 v[232:233], s[62:63], 0, v[132:133]
	s_mov_b32 m0, s21
	v_lshl_add_u64 v[234:235], s[62:63], 0, v[136:137]
	global_load_lds_dwordx4 v[232:233], off
	s_add_i32 m0, s21, 0x2000
	v_lshl_add_u64 v[236:237], s[36:37], 0, v[130:131]
	global_load_lds_dwordx4 v[234:235], off
	s_mov_b32 m0, s44
	v_lshl_add_u64 v[238:239], s[36:37], 0, v[134:135]
	global_load_lds_dwordx4 v[236:237], off
	s_mov_b32 m0, s45
	s_nop 0
	global_load_lds_dwordx4 v[238:239], off
	s_waitcnt vmcnt(8)
	s_waitcnt lgkmcnt(0)
	s_barrier
	s_waitcnt lgkmcnt(0)
	v_mfma_f32_16x16x32_bf16 v[62:65], v[146:149], v[196:199], v[62:65]
	v_mfma_f32_16x16x32_bf16 v[58:61], v[172:175], v[196:199], v[58:61]
	v_mfma_f32_16x16x32_bf16 v[46:49], v[146:149], v[204:207], v[46:49]
	v_mfma_f32_16x16x32_bf16 v[42:45], v[172:175], v[204:207], v[42:45]
	v_mfma_f32_16x16x32_bf16 v[30:33], v[146:149], v[212:215], v[30:33]
	v_mfma_f32_16x16x32_bf16 v[26:29], v[172:175], v[212:215], v[26:29]
	v_mfma_f32_16x16x32_bf16 v[14:17], v[146:149], v[220:223], v[14:17]
	v_mfma_f32_16x16x32_bf16 v[10:13], v[172:175], v[220:223], v[10:13]
	v_mfma_f32_16x16x32_bf16 v[62:65], v[168:171], v[200:203], v[62:65]
	v_mfma_f32_16x16x32_bf16 v[58:61], v[176:179], v[200:203], v[58:61]
	v_mfma_f32_16x16x32_bf16 v[46:49], v[168:171], v[208:211], v[46:49]
	v_mfma_f32_16x16x32_bf16 v[42:45], v[176:179], v[208:211], v[42:45]
	v_mfma_f32_16x16x32_bf16 v[30:33], v[168:171], v[216:219], v[30:33]
	v_mfma_f32_16x16x32_bf16 v[26:29], v[176:179], v[216:219], v[26:29]
	v_mfma_f32_16x16x32_bf16 v[14:17], v[168:171], v[224:227], v[14:17]
	v_mfma_f32_16x16x32_bf16 v[10:13], v[176:179], v[224:227], v[10:13]
	v_mfma_f32_16x16x32_bf16 v[54:57], v[180:183], v[196:199], v[54:57]
	v_mfma_f32_16x16x32_bf16 v[50:53], v[188:191], v[196:199], v[50:53]
	v_mfma_f32_16x16x32_bf16 v[38:41], v[180:183], v[204:207], v[38:41]
	v_mfma_f32_16x16x32_bf16 v[34:37], v[188:191], v[204:207], v[34:37]
	v_mfma_f32_16x16x32_bf16 v[22:25], v[180:183], v[212:215], v[22:25]
	v_mfma_f32_16x16x32_bf16 v[18:21], v[188:191], v[212:215], v[18:21]
	v_mfma_f32_16x16x32_bf16 v[6:9], v[180:183], v[220:223], v[6:9]
	v_mfma_f32_16x16x32_bf16 v[2:5], v[188:191], v[220:223], v[2:5]
	v_mfma_f32_16x16x32_bf16 v[54:57], v[184:187], v[200:203], v[54:57]
	v_mfma_f32_16x16x32_bf16 v[50:53], v[192:195], v[200:203], v[50:53]
	v_mfma_f32_16x16x32_bf16 v[38:41], v[184:187], v[208:211], v[38:41]
	v_mfma_f32_16x16x32_bf16 v[34:37], v[192:195], v[208:211], v[34:37]
	v_mfma_f32_16x16x32_bf16 v[22:25], v[184:187], v[216:219], v[22:25]
	v_mfma_f32_16x16x32_bf16 v[18:21], v[192:195], v[216:219], v[18:21]
	v_mfma_f32_16x16x32_bf16 v[6:9], v[184:187], v[224:227], v[6:9]
	v_mfma_f32_16x16x32_bf16 v[2:5], v[192:195], v[224:227], v[2:5]
	s_barrier
	s_add_i32 s21, 0, 0x18000
	v_add_u32_e32 v167, s21, v162
	s_add_i32 s61, 0, 0x1c000
	ds_read_b128 v[146:149], v167
	ds_read_b128 v[168:171], v167 offset:1024
	ds_read_b128 v[172:175], v167 offset:2048
	ds_read_b128 v[176:179], v167 offset:3072
	v_add_u32_e32 v167, s61, v162
	ds_read_b128 v[180:183], v167
	ds_read_b128 v[184:187], v167 offset:1024
	ds_read_b128 v[188:191], v167 offset:2048
	ds_read_b128 v[192:195], v167 offset:3072
	s_add_u32 s36, s36, 0x150000
	s_addc_u32 s37, s37, 0
	s_mov_b32 m0, s46
	v_lshl_add_u64 v[240:241], s[36:37], 0, v[130:131]
	ds_read_b128 v[196:199], v166 offset:32768
	ds_read_b128 v[200:203], v166 offset:33792
	ds_read_b128 v[204:207], v166 offset:34816
	ds_read_b128 v[208:211], v166 offset:35840
	ds_read_b128 v[212:215], v166 offset:36864
	ds_read_b128 v[216:219], v166 offset:37888
	ds_read_b128 v[220:223], v166 offset:38912
	ds_read_b128 v[224:227], v166 offset:39936
	global_load_lds_dwordx4 v[240:241], off
	v_lshl_add_u64 v[240:241], s[36:37], 0, v[134:135]
	s_mov_b32 m0, s47
	s_nop 0
	global_load_lds_dwordx4 v[240:241], off
	s_waitcnt vmcnt(8)
	s_waitcnt lgkmcnt(0)
	s_barrier
	s_waitcnt lgkmcnt(0)
	v_mfma_f32_16x16x32_bf16 v[126:129], v[146:149], v[196:199], v[126:129]
	v_mfma_f32_16x16x32_bf16 v[122:125], v[172:175], v[196:199], v[122:125]
	v_mfma_f32_16x16x32_bf16 v[110:113], v[146:149], v[204:207], v[110:113]
	v_mfma_f32_16x16x32_bf16 v[106:109], v[172:175], v[204:207], v[106:109]
	v_mfma_f32_16x16x32_bf16 v[94:97], v[146:149], v[212:215], v[94:97]
	v_mfma_f32_16x16x32_bf16 v[90:93], v[172:175], v[212:215], v[90:93]
	v_mfma_f32_16x16x32_bf16 v[78:81], v[146:149], v[220:223], v[78:81]
	v_mfma_f32_16x16x32_bf16 v[74:77], v[172:175], v[220:223], v[74:77]
	v_mfma_f32_16x16x32_bf16 v[126:129], v[168:171], v[200:203], v[126:129]
	v_mfma_f32_16x16x32_bf16 v[122:125], v[176:179], v[200:203], v[122:125]
	v_mfma_f32_16x16x32_bf16 v[110:113], v[168:171], v[208:211], v[110:113]
	v_mfma_f32_16x16x32_bf16 v[106:109], v[176:179], v[208:211], v[106:109]
	v_mfma_f32_16x16x32_bf16 v[94:97], v[168:171], v[216:219], v[94:97]
	v_mfma_f32_16x16x32_bf16 v[90:93], v[176:179], v[216:219], v[90:93]
	v_mfma_f32_16x16x32_bf16 v[78:81], v[168:171], v[224:227], v[78:81]
	v_mfma_f32_16x16x32_bf16 v[74:77], v[176:179], v[224:227], v[74:77]
	v_mfma_f32_16x16x32_bf16 v[118:121], v[180:183], v[196:199], v[118:121]
	v_mfma_f32_16x16x32_bf16 v[114:117], v[188:191], v[196:199], v[114:117]
	v_mfma_f32_16x16x32_bf16 v[102:105], v[180:183], v[204:207], v[102:105]
	v_mfma_f32_16x16x32_bf16 v[98:101], v[188:191], v[204:207], v[98:101]
	v_mfma_f32_16x16x32_bf16 v[86:89], v[180:183], v[212:215], v[86:89]
	v_mfma_f32_16x16x32_bf16 v[82:85], v[188:191], v[212:215], v[82:85]
	v_mfma_f32_16x16x32_bf16 v[70:73], v[180:183], v[220:223], v[70:73]
	v_mfma_f32_16x16x32_bf16 v[66:69], v[188:191], v[220:223], v[66:69]
	v_mfma_f32_16x16x32_bf16 v[118:121], v[184:187], v[200:203], v[118:121]
	v_mfma_f32_16x16x32_bf16 v[114:117], v[192:195], v[200:203], v[114:117]
	v_mfma_f32_16x16x32_bf16 v[102:105], v[184:187], v[208:211], v[102:105]
	v_mfma_f32_16x16x32_bf16 v[98:101], v[192:195], v[208:211], v[98:101]
	v_mfma_f32_16x16x32_bf16 v[86:89], v[184:187], v[216:219], v[86:89]
	v_mfma_f32_16x16x32_bf16 v[82:85], v[192:195], v[216:219], v[82:85]
	v_mfma_f32_16x16x32_bf16 v[70:73], v[184:187], v[224:227], v[70:73]
	v_mfma_f32_16x16x32_bf16 v[66:69], v[192:195], v[224:227], v[66:69]
	s_barrier
	s_add_i32 s21, s21, s43
	v_lshl_add_u64 v[228:229], v[228:229], 0, s[24:25]
	s_mov_b32 m0, s21
	ds_read_b128 v[196:199], v166 offset:49152
	ds_read_b128 v[200:203], v166 offset:50176
	ds_read_b128 v[204:207], v166 offset:51200
	ds_read_b128 v[208:211], v166 offset:52224
	ds_read_b128 v[212:215], v166 offset:53248
	ds_read_b128 v[216:219], v166 offset:54272
	ds_read_b128 v[220:223], v166 offset:55296
	ds_read_b128 v[224:227], v166 offset:56320
	global_load_lds_dwordx4 v[228:229], off
	v_lshl_add_u64 v[228:229], v[230:231], 0, s[24:25]
	s_add_i32 m0, s21, 0x2000
	s_add_i32 s21, s61, s43
	global_load_lds_dwordx4 v[228:229], off
	v_lshl_add_u64 v[228:229], v[232:233], 0, s[24:25]
	s_mov_b32 m0, s21
	s_nop 0
	global_load_lds_dwordx4 v[228:229], off
	v_lshl_add_u64 v[228:229], v[234:235], 0, s[24:25]
	s_add_i32 m0, s21, 0x2000
	s_nop 0
	global_load_lds_dwordx4 v[228:229], off
	v_lshl_add_u64 v[228:229], v[236:237], 0, s[24:25]
	s_mov_b32 m0, s49
	s_nop 0
	global_load_lds_dwordx4 v[228:229], off
	v_lshl_add_u64 v[228:229], v[238:239], 0, s[24:25]
	s_mov_b32 m0, s50
	s_nop 0
	global_load_lds_dwordx4 v[228:229], off
	s_waitcnt vmcnt(8)
	s_waitcnt lgkmcnt(0)
	s_barrier
	s_waitcnt lgkmcnt(0)
	v_mfma_f32_16x16x32_bf16 v[62:65], v[146:149], v[196:199], v[62:65]
	v_mfma_f32_16x16x32_bf16 v[58:61], v[172:175], v[196:199], v[58:61]
	v_mfma_f32_16x16x32_bf16 v[46:49], v[146:149], v[204:207], v[46:49]
	v_mfma_f32_16x16x32_bf16 v[42:45], v[172:175], v[204:207], v[42:45]
	v_mfma_f32_16x16x32_bf16 v[30:33], v[146:149], v[212:215], v[30:33]
	v_mfma_f32_16x16x32_bf16 v[26:29], v[172:175], v[212:215], v[26:29]
	v_mfma_f32_16x16x32_bf16 v[14:17], v[146:149], v[220:223], v[14:17]
	v_mfma_f32_16x16x32_bf16 v[10:13], v[172:175], v[220:223], v[10:13]
	v_mfma_f32_16x16x32_bf16 v[62:65], v[168:171], v[200:203], v[62:65]
	v_mfma_f32_16x16x32_bf16 v[58:61], v[176:179], v[200:203], v[58:61]
	v_mfma_f32_16x16x32_bf16 v[46:49], v[168:171], v[208:211], v[46:49]
	v_mfma_f32_16x16x32_bf16 v[42:45], v[176:179], v[208:211], v[42:45]
	v_mfma_f32_16x16x32_bf16 v[30:33], v[168:171], v[216:219], v[30:33]
	v_mfma_f32_16x16x32_bf16 v[26:29], v[176:179], v[216:219], v[26:29]
	v_mfma_f32_16x16x32_bf16 v[14:17], v[168:171], v[224:227], v[14:17]
	v_mfma_f32_16x16x32_bf16 v[10:13], v[176:179], v[224:227], v[10:13]
	v_mfma_f32_16x16x32_bf16 v[54:57], v[180:183], v[196:199], v[54:57]
	v_mfma_f32_16x16x32_bf16 v[50:53], v[188:191], v[196:199], v[50:53]
	v_mfma_f32_16x16x32_bf16 v[38:41], v[180:183], v[204:207], v[38:41]
	v_mfma_f32_16x16x32_bf16 v[34:37], v[188:191], v[204:207], v[34:37]
	v_mfma_f32_16x16x32_bf16 v[22:25], v[180:183], v[212:215], v[22:25]
	v_mfma_f32_16x16x32_bf16 v[18:21], v[188:191], v[212:215], v[18:21]
	v_mfma_f32_16x16x32_bf16 v[6:9], v[180:183], v[220:223], v[6:9]
	v_mfma_f32_16x16x32_bf16 v[2:5], v[188:191], v[220:223], v[2:5]
	v_mfma_f32_16x16x32_bf16 v[54:57], v[184:187], v[200:203], v[54:57]
	v_mfma_f32_16x16x32_bf16 v[50:53], v[192:195], v[200:203], v[50:53]
	v_mfma_f32_16x16x32_bf16 v[38:41], v[184:187], v[208:211], v[38:41]
	v_mfma_f32_16x16x32_bf16 v[34:37], v[192:195], v[208:211], v[34:37]
	v_mfma_f32_16x16x32_bf16 v[22:25], v[184:187], v[216:219], v[22:25]
	v_mfma_f32_16x16x32_bf16 v[18:21], v[192:195], v[216:219], v[18:21]
	v_mfma_f32_16x16x32_bf16 v[6:9], v[184:187], v[224:227], v[6:9]
	v_mfma_f32_16x16x32_bf16 v[2:5], v[192:195], v[224:227], v[2:5]
	s_barrier
	s_add_u32 s34, s34, 0x100
	s_addc_u32 s35, s35, 0
	s_add_u32 s10, s10, 0x100
	s_addc_u32 s20, s20, 0
	s_cmp_ge_i32 s60, s51
	s_mov_b32 s21, s60
	s_cbranch_scc0 .LBB0_502

.LBB0_528:
	ds_read_b128 v[146:149], v1
	ds_read_b128 v[156:159], v1 offset:1024
	ds_read_b128 v[160:163], v1 offset:2048
	ds_read_b128 v[164:167], v1 offset:3072
	ds_read_b128 v[168:171], v150
	ds_read_b128 v[172:175], v150 offset:1024
	ds_read_b128 v[176:179], v150 offset:2048
	ds_read_b128 v[180:183], v150 offset:3072
	s_add_u32 s26, s4, 0xffeb0080
	s_addc_u32 s27, s5, -1
	s_cmp_eq_u32 s51, 12
	s_cselect_b32 s29, s23, s27
	s_cselect_b32 s28, s22, s26
	s_cselect_b32 s27, s10, s21
	s_cselect_b32 s26, s19, s20
	v_lshl_add_u64 v[216:217], s[4:5], 0, v[138:139]
	s_add_i32 m0, s38, 0xc000
	ds_read_b128 v[184:187], v153
	ds_read_b128 v[188:191], v153 offset:1024
	ds_read_b128 v[192:195], v153 offset:2048
	ds_read_b128 v[196:199], v153 offset:3072
	ds_read_b128 v[200:203], v153 offset:4096
	ds_read_b128 v[204:207], v153 offset:5120
	ds_read_b128 v[208:211], v153 offset:6144
	ds_read_b128 v[212:215], v153 offset:7168
	global_load_lds_dwordx4 v[216:217], off
	v_lshl_add_u64 v[216:217], s[4:5], 0, v[140:141]
	s_add_i32 m0, s38, 0xe000
	s_nop 0
	global_load_lds_dwordx4 v[216:217], off
	s_waitcnt vmcnt(8)
	s_waitcnt lgkmcnt(0)
	s_barrier
	s_waitcnt lgkmcnt(0)
	v_mfma_f32_16x16x32_bf16 v[126:129], v[146:149], v[184:187], v[126:129]
	v_mfma_f32_16x16x32_bf16 v[122:125], v[160:163], v[184:187], v[122:125]
	v_mfma_f32_16x16x32_bf16 v[110:113], v[146:149], v[192:195], v[110:113]
	v_mfma_f32_16x16x32_bf16 v[106:109], v[160:163], v[192:195], v[106:109]
	v_mfma_f32_16x16x32_bf16 v[94:97], v[146:149], v[200:203], v[94:97]
	v_mfma_f32_16x16x32_bf16 v[90:93], v[160:163], v[200:203], v[90:93]
	v_mfma_f32_16x16x32_bf16 v[78:81], v[146:149], v[208:211], v[78:81]
	v_mfma_f32_16x16x32_bf16 v[74:77], v[160:163], v[208:211], v[74:77]
	v_mfma_f32_16x16x32_bf16 v[126:129], v[156:159], v[188:191], v[126:129]
	v_mfma_f32_16x16x32_bf16 v[122:125], v[164:167], v[188:191], v[122:125]
	v_mfma_f32_16x16x32_bf16 v[110:113], v[156:159], v[196:199], v[110:113]
	v_mfma_f32_16x16x32_bf16 v[106:109], v[164:167], v[196:199], v[106:109]
	v_mfma_f32_16x16x32_bf16 v[94:97], v[156:159], v[204:207], v[94:97]
	v_mfma_f32_16x16x32_bf16 v[90:93], v[164:167], v[204:207], v[90:93]
	v_mfma_f32_16x16x32_bf16 v[78:81], v[156:159], v[212:215], v[78:81]
	v_mfma_f32_16x16x32_bf16 v[74:77], v[164:167], v[212:215], v[74:77]
	v_mfma_f32_16x16x32_bf16 v[118:121], v[168:171], v[184:187], v[118:121]
	v_mfma_f32_16x16x32_bf16 v[114:117], v[176:179], v[184:187], v[114:117]
	v_mfma_f32_16x16x32_bf16 v[102:105], v[168:171], v[192:195], v[102:105]
	v_mfma_f32_16x16x32_bf16 v[98:101], v[176:179], v[192:195], v[98:101]
	v_mfma_f32_16x16x32_bf16 v[86:89], v[168:171], v[200:203], v[86:89]
	v_mfma_f32_16x16x32_bf16 v[82:85], v[176:179], v[200:203], v[82:85]
	v_mfma_f32_16x16x32_bf16 v[70:73], v[168:171], v[208:211], v[70:73]
	v_mfma_f32_16x16x32_bf16 v[66:69], v[176:179], v[208:211], v[66:69]
	v_mfma_f32_16x16x32_bf16 v[118:121], v[172:175], v[188:191], v[118:121]
	v_mfma_f32_16x16x32_bf16 v[114:117], v[180:183], v[188:191], v[114:117]
	v_mfma_f32_16x16x32_bf16 v[102:105], v[172:175], v[196:199], v[102:105]
	v_mfma_f32_16x16x32_bf16 v[98:101], v[180:183], v[196:199], v[98:101]
	v_mfma_f32_16x16x32_bf16 v[86:89], v[172:175], v[204:207], v[86:89]
	v_mfma_f32_16x16x32_bf16 v[82:85], v[180:183], v[204:207], v[82:85]
	v_mfma_f32_16x16x32_bf16 v[70:73], v[172:175], v[212:215], v[70:73]
	v_mfma_f32_16x16x32_bf16 v[66:69], v[180:183], v[212:215], v[66:69]
	s_barrier
	s_add_i32 s52, s46, s31
	v_lshl_add_u64 v[216:217], s[26:27], 0, v[132:133]
	s_mov_b32 m0, s52
	ds_read_b128 v[184:187], v153 offset:16384
	ds_read_b128 v[188:191], v153 offset:17408
	ds_read_b128 v[192:195], v153 offset:18432
	ds_read_b128 v[196:199], v153 offset:19456
	ds_read_b128 v[200:203], v153 offset:20480
	ds_read_b128 v[204:207], v153 offset:21504
	ds_read_b128 v[208:211], v153 offset:22528
	ds_read_b128 v[212:215], v153 offset:23552
	global_load_lds_dwordx4 v[216:217], off
	s_add_i32 m0, s52, 0x2000
	s_add_u32 s52, s26, 0x40000
	v_lshl_add_u64 v[218:219], s[26:27], 0, v[136:137]
	s_addc_u32 s53, s27, 0
	s_add_i32 s54, s47, s31
	global_load_lds_dwordx4 v[218:219], off
	v_lshl_add_u64 v[220:221], s[52:53], 0, v[132:133]
	s_mov_b32 m0, s54
	v_lshl_add_u64 v[222:223], s[28:29], 0, v[134:135]
	global_load_lds_dwordx4 v[220:221], off
	v_lshl_add_u64 v[220:221], s[52:53], 0, v[136:137]
	s_add_i32 m0, s54, 0x2000
	s_nop 0
	global_load_lds_dwordx4 v[220:221], off
	v_lshl_add_u64 v[220:221], s[28:29], 0, v[130:131]
	s_mov_b32 m0, s38
	s_nop 0
	global_load_lds_dwordx4 v[220:221], off
	s_mov_b32 m0, s39
	s_nop 0
	global_load_lds_dwordx4 v[222:223], off
	s_waitcnt vmcnt(8)
	s_waitcnt lgkmcnt(0)
	s_barrier
	s_waitcnt lgkmcnt(0)
	v_mfma_f32_16x16x32_bf16 v[62:65], v[146:149], v[184:187], v[62:65]
	v_mfma_f32_16x16x32_bf16 v[58:61], v[160:163], v[184:187], v[58:61]
	v_mfma_f32_16x16x32_bf16 v[46:49], v[146:149], v[192:195], v[46:49]
	v_mfma_f32_16x16x32_bf16 v[42:45], v[160:163], v[192:195], v[42:45]
	v_mfma_f32_16x16x32_bf16 v[30:33], v[146:149], v[200:203], v[30:33]
	v_mfma_f32_16x16x32_bf16 v[26:29], v[160:163], v[200:203], v[26:29]
	v_mfma_f32_16x16x32_bf16 v[14:17], v[146:149], v[208:211], v[14:17]
	v_mfma_f32_16x16x32_bf16 v[10:13], v[160:163], v[208:211], v[10:13]
	v_mfma_f32_16x16x32_bf16 v[62:65], v[156:159], v[188:191], v[62:65]
	v_mfma_f32_16x16x32_bf16 v[58:61], v[164:167], v[188:191], v[58:61]
	v_mfma_f32_16x16x32_bf16 v[46:49], v[156:159], v[196:199], v[46:49]
	v_mfma_f32_16x16x32_bf16 v[42:45], v[164:167], v[196:199], v[42:45]
	v_mfma_f32_16x16x32_bf16 v[30:33], v[156:159], v[204:207], v[30:33]
	v_mfma_f32_16x16x32_bf16 v[26:29], v[164:167], v[204:207], v[26:29]
	v_mfma_f32_16x16x32_bf16 v[14:17], v[156:159], v[212:215], v[14:17]
	v_mfma_f32_16x16x32_bf16 v[10:13], v[164:167], v[212:215], v[10:13]
	v_mfma_f32_16x16x32_bf16 v[54:57], v[168:171], v[184:187], v[54:57]
	v_mfma_f32_16x16x32_bf16 v[50:53], v[176:179], v[184:187], v[50:53]
	v_mfma_f32_16x16x32_bf16 v[38:41], v[168:171], v[192:195], v[38:41]
	v_mfma_f32_16x16x32_bf16 v[34:37], v[176:179], v[192:195], v[34:37]
	v_mfma_f32_16x16x32_bf16 v[22:25], v[168:171], v[200:203], v[22:25]
	v_mfma_f32_16x16x32_bf16 v[18:21], v[176:179], v[200:203], v[18:21]
	v_mfma_f32_16x16x32_bf16 v[6:9], v[168:171], v[208:211], v[6:9]
	v_mfma_f32_16x16x32_bf16 v[2:5], v[176:179], v[208:211], v[2:5]
	v_mfma_f32_16x16x32_bf16 v[54:57], v[172:175], v[188:191], v[54:57]
	v_mfma_f32_16x16x32_bf16 v[50:53], v[180:183], v[188:191], v[50:53]
	v_mfma_f32_16x16x32_bf16 v[38:41], v[172:175], v[196:199], v[38:41]
	v_mfma_f32_16x16x32_bf16 v[34:37], v[180:183], v[196:199], v[34:37]
	v_mfma_f32_16x16x32_bf16 v[22:25], v[172:175], v[204:207], v[22:25]
	v_mfma_f32_16x16x32_bf16 v[18:21], v[180:183], v[204:207], v[18:21]
	v_mfma_f32_16x16x32_bf16 v[6:9], v[172:175], v[212:215], v[6:9]
	v_mfma_f32_16x16x32_bf16 v[2:5], v[180:183], v[212:215], v[2:5]
	s_barrier
	s_add_i32 s52, 0, 0x18000
	v_add_u32_e32 v154, s52, v152
	s_add_i32 s53, 0, 0x1c000
	ds_read_b128 v[146:149], v154
	ds_read_b128 v[156:159], v154 offset:1024
	ds_read_b128 v[160:163], v154 offset:2048
	ds_read_b128 v[164:167], v154 offset:3072
	v_add_u32_e32 v154, s53, v152
	ds_read_b128 v[168:171], v154
	ds_read_b128 v[172:175], v154 offset:1024
	ds_read_b128 v[176:179], v154 offset:2048
	ds_read_b128 v[180:183], v154 offset:3072
	s_add_u32 s28, s28, 0x150000
	s_addc_u32 s29, s29, 0
	s_mov_b32 m0, s40
	v_lshl_add_u64 v[224:225], s[28:29], 0, v[130:131]
	ds_read_b128 v[184:187], v153 offset:32768
	ds_read_b128 v[188:191], v153 offset:33792
	ds_read_b128 v[192:195], v153 offset:34816
	ds_read_b128 v[196:199], v153 offset:35840
	ds_read_b128 v[200:203], v153 offset:36864
	ds_read_b128 v[204:207], v153 offset:37888
	ds_read_b128 v[208:211], v153 offset:38912
	ds_read_b128 v[212:215], v153 offset:39936
	global_load_lds_dwordx4 v[224:225], off
	v_lshl_add_u64 v[224:225], s[28:29], 0, v[134:135]
	s_mov_b32 m0, s41
	s_nop 0
	global_load_lds_dwordx4 v[224:225], off
	s_waitcnt vmcnt(8)
	s_waitcnt lgkmcnt(0)
	s_barrier
	s_waitcnt lgkmcnt(0)
	v_mfma_f32_16x16x32_bf16 v[126:129], v[146:149], v[184:187], v[126:129]
	v_mfma_f32_16x16x32_bf16 v[122:125], v[160:163], v[184:187], v[122:125]
	v_mfma_f32_16x16x32_bf16 v[110:113], v[146:149], v[192:195], v[110:113]
	v_mfma_f32_16x16x32_bf16 v[106:109], v[160:163], v[192:195], v[106:109]
	v_mfma_f32_16x16x32_bf16 v[94:97], v[146:149], v[200:203], v[94:97]
	v_mfma_f32_16x16x32_bf16 v[90:93], v[160:163], v[200:203], v[90:93]
	v_mfma_f32_16x16x32_bf16 v[78:81], v[146:149], v[208:211], v[78:81]
	v_mfma_f32_16x16x32_bf16 v[74:77], v[160:163], v[208:211], v[74:77]
	v_mfma_f32_16x16x32_bf16 v[126:129], v[156:159], v[188:191], v[126:129]
	v_mfma_f32_16x16x32_bf16 v[122:125], v[164:167], v[188:191], v[122:125]
	v_mfma_f32_16x16x32_bf16 v[110:113], v[156:159], v[196:199], v[110:113]
	v_mfma_f32_16x16x32_bf16 v[106:109], v[164:167], v[196:199], v[106:109]
	v_mfma_f32_16x16x32_bf16 v[94:97], v[156:159], v[204:207], v[94:97]
	v_mfma_f32_16x16x32_bf16 v[90:93], v[164:167], v[204:207], v[90:93]
	v_mfma_f32_16x16x32_bf16 v[78:81], v[156:159], v[212:215], v[78:81]
	v_mfma_f32_16x16x32_bf16 v[74:77], v[164:167], v[212:215], v[74:77]
	v_mfma_f32_16x16x32_bf16 v[118:121], v[168:171], v[184:187], v[118:121]
	v_mfma_f32_16x16x32_bf16 v[114:117], v[176:179], v[184:187], v[114:117]
	v_mfma_f32_16x16x32_bf16 v[102:105], v[168:171], v[192:195], v[102:105]
	v_mfma_f32_16x16x32_bf16 v[98:101], v[176:179], v[192:195], v[98:101]
	v_mfma_f32_16x16x32_bf16 v[86:89], v[168:171], v[200:203], v[86:89]
	v_mfma_f32_16x16x32_bf16 v[82:85], v[176:179], v[200:203], v[82:85]
	v_mfma_f32_16x16x32_bf16 v[70:73], v[168:171], v[208:211], v[70:73]
	v_mfma_f32_16x16x32_bf16 v[66:69], v[176:179], v[208:211], v[66:69]
	v_mfma_f32_16x16x32_bf16 v[118:121], v[172:175], v[188:191], v[118:121]
	v_mfma_f32_16x16x32_bf16 v[114:117], v[180:183], v[188:191], v[114:117]
	v_mfma_f32_16x16x32_bf16 v[102:105], v[172:175], v[196:199], v[102:105]
	v_mfma_f32_16x16x32_bf16 v[98:101], v[180:183], v[196:199], v[98:101]
	v_mfma_f32_16x16x32_bf16 v[86:89], v[172:175], v[204:207], v[86:89]
	v_mfma_f32_16x16x32_bf16 v[82:85], v[180:183], v[204:207], v[82:85]
	v_mfma_f32_16x16x32_bf16 v[70:73], v[172:175], v[212:215], v[70:73]
	v_mfma_f32_16x16x32_bf16 v[66:69], v[180:183], v[212:215], v[66:69]
	s_barrier
	s_add_i32 s28, s52, s31
	v_lshl_add_u64 v[216:217], v[216:217], 0, s[14:15]
	s_mov_b32 m0, s28
	ds_read_b128 v[184:187], v153 offset:49152
	ds_read_b128 v[188:191], v153 offset:50176
	ds_read_b128 v[192:195], v153 offset:51200
	ds_read_b128 v[196:199], v153 offset:52224
	ds_read_b128 v[200:203], v153 offset:53248
	ds_read_b128 v[204:207], v153 offset:54272
	ds_read_b128 v[208:211], v153 offset:55296
	ds_read_b128 v[212:215], v153 offset:56320
	global_load_lds_dwordx4 v[216:217], off
	s_add_i32 m0, s28, 0x2000
	s_add_u32 s26, s26, 0x40080
	v_lshl_add_u64 v[216:217], v[218:219], 0, s[14:15]
	s_addc_u32 s27, s27, 0
	s_add_i32 s28, s53, s31
	global_load_lds_dwordx4 v[216:217], off
	v_lshl_add_u64 v[216:217], s[26:27], 0, v[132:133]
	s_mov_b32 m0, s28
	s_nop 0
	global_load_lds_dwordx4 v[216:217], off
	v_lshl_add_u64 v[216:217], s[26:27], 0, v[136:137]
	s_add_i32 m0, s28, 0x2000
	s_nop 0
	global_load_lds_dwordx4 v[216:217], off
	v_lshl_add_u64 v[216:217], v[220:221], 0, s[14:15]
	s_mov_b32 m0, s43
	s_nop 0
	global_load_lds_dwordx4 v[216:217], off
	v_lshl_add_u64 v[216:217], v[222:223], 0, s[14:15]
	s_mov_b32 m0, s44
	s_nop 0
	global_load_lds_dwordx4 v[216:217], off
	s_waitcnt vmcnt(8)
	s_waitcnt lgkmcnt(0)
	s_barrier
	s_waitcnt lgkmcnt(0)
	v_mfma_f32_16x16x32_bf16 v[62:65], v[146:149], v[184:187], v[62:65]
	v_mfma_f32_16x16x32_bf16 v[58:61], v[160:163], v[184:187], v[58:61]
	v_mfma_f32_16x16x32_bf16 v[46:49], v[146:149], v[192:195], v[46:49]
	v_mfma_f32_16x16x32_bf16 v[42:45], v[160:163], v[192:195], v[42:45]
	v_mfma_f32_16x16x32_bf16 v[30:33], v[146:149], v[200:203], v[30:33]
	v_mfma_f32_16x16x32_bf16 v[26:29], v[160:163], v[200:203], v[26:29]
	v_mfma_f32_16x16x32_bf16 v[14:17], v[146:149], v[208:211], v[14:17]
	v_mfma_f32_16x16x32_bf16 v[10:13], v[160:163], v[208:211], v[10:13]
	v_mfma_f32_16x16x32_bf16 v[62:65], v[156:159], v[188:191], v[62:65]
	v_mfma_f32_16x16x32_bf16 v[58:61], v[164:167], v[188:191], v[58:61]
	v_mfma_f32_16x16x32_bf16 v[46:49], v[156:159], v[196:199], v[46:49]
	v_mfma_f32_16x16x32_bf16 v[42:45], v[164:167], v[196:199], v[42:45]
	v_mfma_f32_16x16x32_bf16 v[30:33], v[156:159], v[204:207], v[30:33]
	v_mfma_f32_16x16x32_bf16 v[26:29], v[164:167], v[204:207], v[26:29]
	v_mfma_f32_16x16x32_bf16 v[14:17], v[156:159], v[212:215], v[14:17]
	v_mfma_f32_16x16x32_bf16 v[10:13], v[164:167], v[212:215], v[10:13]
	v_mfma_f32_16x16x32_bf16 v[54:57], v[168:171], v[184:187], v[54:57]
	v_mfma_f32_16x16x32_bf16 v[50:53], v[176:179], v[184:187], v[50:53]
	v_mfma_f32_16x16x32_bf16 v[38:41], v[168:171], v[192:195], v[38:41]
	v_mfma_f32_16x16x32_bf16 v[34:37], v[176:179], v[192:195], v[34:37]
	v_mfma_f32_16x16x32_bf16 v[22:25], v[168:171], v[200:203], v[22:25]
	v_mfma_f32_16x16x32_bf16 v[18:21], v[176:179], v[200:203], v[18:21]
	v_mfma_f32_16x16x32_bf16 v[6:9], v[168:171], v[208:211], v[6:9]
	v_mfma_f32_16x16x32_bf16 v[2:5], v[176:179], v[208:211], v[2:5]
	v_mfma_f32_16x16x32_bf16 v[54:57], v[172:175], v[188:191], v[54:57]
	v_mfma_f32_16x16x32_bf16 v[50:53], v[180:183], v[188:191], v[50:53]
	v_mfma_f32_16x16x32_bf16 v[38:41], v[172:175], v[196:199], v[38:41]
	v_mfma_f32_16x16x32_bf16 v[34:37], v[180:183], v[196:199], v[34:37]
	v_mfma_f32_16x16x32_bf16 v[22:25], v[172:175], v[204:207], v[22:25]
	v_mfma_f32_16x16x32_bf16 v[18:21], v[180:183], v[204:207], v[18:21]
	v_mfma_f32_16x16x32_bf16 v[6:9], v[172:175], v[212:215], v[6:9]
	v_mfma_f32_16x16x32_bf16 v[2:5], v[180:183], v[212:215], v[2:5]
	s_barrier
	s_add_i32 s51, s51, 2
	s_add_u32 s4, s4, 0x100
	s_addc_u32 s5, s5, 0
	s_add_u32 s20, s20, 0x100
	s_addc_u32 s21, s21, 0
	s_cmp_gt_u32 s51, 13
	s_cbranch_scc0 .LBB0_528
	s_and_b64 vcc, exec, s[16:17]
	s_cbranch_vccz .LBB0_531
	s_barrier

.LBB0_576:
	ds_read_b128 v[152:155], v148
	ds_read_b128 v[156:159], v148 offset:1024
	ds_read_b128 v[160:163], v148 offset:2048
	ds_read_b128 v[164:167], v148 offset:3072
	ds_read_b128 v[168:171], v149
	ds_read_b128 v[172:175], v149 offset:1024
	ds_read_b128 v[176:179], v149 offset:2048
	ds_read_b128 v[180:183], v149 offset:3072
	s_add_u32 s38, s36, 0xfffc0080
	s_addc_u32 s39, s37, -1
	s_cmp_eq_u32 s63, 12
	s_cselect_b32 s41, s10, s39
	s_cselect_b32 s40, s20, s38
	s_cselect_b32 s39, s21, s62
	s_cselect_b32 s38, s27, s29
	v_lshl_add_u64 v[216:217], s[36:37], 0, v[138:139]
	s_add_i32 m0, s25, 0xc000
	ds_read_b128 v[184:187], v150
	ds_read_b128 v[188:191], v150 offset:1024
	ds_read_b128 v[192:195], v150 offset:2048
	ds_read_b128 v[196:199], v150 offset:3072
	ds_read_b128 v[200:203], v150 offset:4096
	ds_read_b128 v[204:207], v150 offset:5120
	ds_read_b128 v[208:211], v150 offset:6144
	ds_read_b128 v[212:215], v150 offset:7168
	global_load_lds_dwordx4 v[216:217], off
	v_lshl_add_u64 v[216:217], s[36:37], 0, v[140:141]
	s_add_i32 m0, s25, 0xe000
	s_nop 0
	global_load_lds_dwordx4 v[216:217], off
	s_waitcnt vmcnt(8)
	s_waitcnt lgkmcnt(0)
	s_barrier
	s_waitcnt lgkmcnt(0)
	v_mfma_f32_16x16x32_bf16 v[126:129], v[152:155], v[184:187], v[126:129]
	v_mfma_f32_16x16x32_bf16 v[122:125], v[160:163], v[184:187], v[122:125]
	v_mfma_f32_16x16x32_bf16 v[118:121], v[152:155], v[192:195], v[118:121]
	v_mfma_f32_16x16x32_bf16 v[114:117], v[160:163], v[192:195], v[114:117]
	v_mfma_f32_16x16x32_bf16 v[102:105], v[152:155], v[200:203], v[102:105]
	v_mfma_f32_16x16x32_bf16 v[98:101], v[160:163], v[200:203], v[98:101]
	v_mfma_f32_16x16x32_bf16 v[86:89], v[152:155], v[208:211], v[86:89]
	v_mfma_f32_16x16x32_bf16 v[82:85], v[160:163], v[208:211], v[82:85]
	v_mfma_f32_16x16x32_bf16 v[126:129], v[156:159], v[188:191], v[126:129]
	v_mfma_f32_16x16x32_bf16 v[122:125], v[164:167], v[188:191], v[122:125]
	v_mfma_f32_16x16x32_bf16 v[118:121], v[156:159], v[196:199], v[118:121]
	v_mfma_f32_16x16x32_bf16 v[114:117], v[164:167], v[196:199], v[114:117]
	v_mfma_f32_16x16x32_bf16 v[102:105], v[156:159], v[204:207], v[102:105]
	v_mfma_f32_16x16x32_bf16 v[98:101], v[164:167], v[204:207], v[98:101]
	v_mfma_f32_16x16x32_bf16 v[86:89], v[156:159], v[212:215], v[86:89]
	v_mfma_f32_16x16x32_bf16 v[82:85], v[164:167], v[212:215], v[82:85]
	v_mfma_f32_16x16x32_bf16 v[110:113], v[168:171], v[184:187], v[110:113]
	v_mfma_f32_16x16x32_bf16 v[106:109], v[176:179], v[184:187], v[106:109]
	v_mfma_f32_16x16x32_bf16 v[94:97], v[168:171], v[192:195], v[94:97]
	v_mfma_f32_16x16x32_bf16 v[90:93], v[176:179], v[192:195], v[90:93]
	v_mfma_f32_16x16x32_bf16 v[78:81], v[168:171], v[200:203], v[78:81]
	v_mfma_f32_16x16x32_bf16 v[74:77], v[176:179], v[200:203], v[74:77]
	v_mfma_f32_16x16x32_bf16 v[70:73], v[168:171], v[208:211], v[70:73]
	v_mfma_f32_16x16x32_bf16 v[66:69], v[176:179], v[208:211], v[66:69]
	v_mfma_f32_16x16x32_bf16 v[110:113], v[172:175], v[188:191], v[110:113]
	v_mfma_f32_16x16x32_bf16 v[106:109], v[180:183], v[188:191], v[106:109]
	v_mfma_f32_16x16x32_bf16 v[94:97], v[172:175], v[196:199], v[94:97]
	v_mfma_f32_16x16x32_bf16 v[90:93], v[180:183], v[196:199], v[90:93]
	v_mfma_f32_16x16x32_bf16 v[78:81], v[172:175], v[204:207], v[78:81]
	v_mfma_f32_16x16x32_bf16 v[74:77], v[180:183], v[204:207], v[74:77]
	v_mfma_f32_16x16x32_bf16 v[70:73], v[172:175], v[212:215], v[70:73]
	v_mfma_f32_16x16x32_bf16 v[66:69], v[180:183], v[212:215], v[66:69]
	s_barrier
	s_add_i32 s64, s55, s47
	v_lshl_add_u64 v[216:217], s[38:39], 0, v[132:133]
	s_mov_b32 m0, s64
	ds_read_b128 v[184:187], v150 offset:16384
	ds_read_b128 v[188:191], v150 offset:17408
	ds_read_b128 v[192:195], v150 offset:18432
	ds_read_b128 v[196:199], v150 offset:19456
	ds_read_b128 v[200:203], v150 offset:20480
	ds_read_b128 v[204:207], v150 offset:21504
	ds_read_b128 v[208:211], v150 offset:22528
	ds_read_b128 v[212:215], v150 offset:23552
	global_load_lds_dwordx4 v[216:217], off
	s_add_i32 m0, s64, 0x2000
	s_add_u32 s64, s38, 0x40000
	v_lshl_add_u64 v[218:219], s[38:39], 0, v[136:137]
	s_addc_u32 s65, s39, 0
	s_add_i32 s66, s56, s47
	global_load_lds_dwordx4 v[218:219], off
	v_lshl_add_u64 v[220:221], s[64:65], 0, v[132:133]
	s_mov_b32 m0, s66
	v_lshl_add_u64 v[222:223], s[40:41], 0, v[134:135]
	global_load_lds_dwordx4 v[220:221], off
	v_lshl_add_u64 v[220:221], s[64:65], 0, v[136:137]
	s_add_i32 m0, s66, 0x2000
	s_nop 0
	global_load_lds_dwordx4 v[220:221], off
	v_lshl_add_u64 v[220:221], s[40:41], 0, v[130:131]
	s_mov_b32 m0, s25
	s_nop 0
	global_load_lds_dwordx4 v[220:221], off
	s_mov_b32 m0, s48
	s_nop 0
	global_load_lds_dwordx4 v[222:223], off
	s_waitcnt vmcnt(8)
	s_waitcnt lgkmcnt(0)
	s_barrier
	s_waitcnt lgkmcnt(0)
	v_mfma_f32_16x16x32_bf16 v[62:65], v[152:155], v[184:187], v[62:65]
	v_mfma_f32_16x16x32_bf16 v[58:61], v[160:163], v[184:187], v[58:61]
	v_mfma_f32_16x16x32_bf16 v[54:57], v[152:155], v[192:195], v[54:57]
	v_mfma_f32_16x16x32_bf16 v[50:53], v[160:163], v[192:195], v[50:53]
	v_mfma_f32_16x16x32_bf16 v[38:41], v[152:155], v[200:203], v[38:41]
	v_mfma_f32_16x16x32_bf16 v[34:37], v[160:163], v[200:203], v[34:37]
	v_mfma_f32_16x16x32_bf16 v[22:25], v[152:155], v[208:211], v[22:25]
	v_mfma_f32_16x16x32_bf16 v[18:21], v[160:163], v[208:211], v[18:21]
	v_mfma_f32_16x16x32_bf16 v[62:65], v[156:159], v[188:191], v[62:65]
	v_mfma_f32_16x16x32_bf16 v[58:61], v[164:167], v[188:191], v[58:61]
	v_mfma_f32_16x16x32_bf16 v[54:57], v[156:159], v[196:199], v[54:57]
	v_mfma_f32_16x16x32_bf16 v[50:53], v[164:167], v[196:199], v[50:53]
	v_mfma_f32_16x16x32_bf16 v[38:41], v[156:159], v[204:207], v[38:41]
	v_mfma_f32_16x16x32_bf16 v[34:37], v[164:167], v[204:207], v[34:37]
	v_mfma_f32_16x16x32_bf16 v[22:25], v[156:159], v[212:215], v[22:25]
	v_mfma_f32_16x16x32_bf16 v[18:21], v[164:167], v[212:215], v[18:21]
	v_mfma_f32_16x16x32_bf16 v[46:49], v[168:171], v[184:187], v[46:49]
	v_mfma_f32_16x16x32_bf16 v[42:45], v[176:179], v[184:187], v[42:45]
	v_mfma_f32_16x16x32_bf16 v[30:33], v[168:171], v[192:195], v[30:33]
	v_mfma_f32_16x16x32_bf16 v[26:29], v[176:179], v[192:195], v[26:29]
	v_mfma_f32_16x16x32_bf16 v[14:17], v[168:171], v[200:203], v[14:17]
	v_mfma_f32_16x16x32_bf16 v[10:13], v[176:179], v[200:203], v[10:13]
	v_mfma_f32_16x16x32_bf16 v[6:9], v[168:171], v[208:211], v[6:9]
	v_mfma_f32_16x16x32_bf16 v[2:5], v[176:179], v[208:211], v[2:5]
	v_mfma_f32_16x16x32_bf16 v[46:49], v[172:175], v[188:191], v[46:49]
	v_mfma_f32_16x16x32_bf16 v[42:45], v[180:183], v[188:191], v[42:45]
	v_mfma_f32_16x16x32_bf16 v[30:33], v[172:175], v[196:199], v[30:33]
	v_mfma_f32_16x16x32_bf16 v[26:29], v[180:183], v[196:199], v[26:29]
	v_mfma_f32_16x16x32_bf16 v[14:17], v[172:175], v[204:207], v[14:17]
	v_mfma_f32_16x16x32_bf16 v[10:13], v[180:183], v[204:207], v[10:13]
	v_mfma_f32_16x16x32_bf16 v[6:9], v[172:175], v[212:215], v[6:9]
	v_mfma_f32_16x16x32_bf16 v[2:5], v[180:183], v[212:215], v[2:5]
	s_barrier
	s_add_i32 s64, 0, 0x18000
	v_add_u32_e32 v151, s64, v146
	s_add_i32 s65, 0, 0x1c000
	ds_read_b128 v[152:155], v151
	ds_read_b128 v[156:159], v151 offset:1024
	ds_read_b128 v[160:163], v151 offset:2048
	ds_read_b128 v[164:167], v151 offset:3072
	v_add_u32_e32 v151, s65, v146
	ds_read_b128 v[168:171], v151
	ds_read_b128 v[172:175], v151 offset:1024
	ds_read_b128 v[176:179], v151 offset:2048
	ds_read_b128 v[180:183], v151 offset:3072
	s_add_u32 s40, s40, 0x40000
	s_addc_u32 s41, s41, 0
	s_mov_b32 m0, s49
	v_lshl_add_u64 v[224:225], s[40:41], 0, v[130:131]
	ds_read_b128 v[184:187], v150 offset:32768
	ds_read_b128 v[188:191], v150 offset:33792
	ds_read_b128 v[192:195], v150 offset:34816
	ds_read_b128 v[196:199], v150 offset:35840
	ds_read_b128 v[200:203], v150 offset:36864
	ds_read_b128 v[204:207], v150 offset:37888
	ds_read_b128 v[208:211], v150 offset:38912
	ds_read_b128 v[212:215], v150 offset:39936
	global_load_lds_dwordx4 v[224:225], off
	v_lshl_add_u64 v[224:225], s[40:41], 0, v[134:135]
	s_mov_b32 m0, s50
	s_nop 0
	global_load_lds_dwordx4 v[224:225], off
	s_waitcnt vmcnt(8)
	s_waitcnt lgkmcnt(0)
	s_barrier
	s_waitcnt lgkmcnt(0)
	v_mfma_f32_16x16x32_bf16 v[126:129], v[152:155], v[184:187], v[126:129]
	v_mfma_f32_16x16x32_bf16 v[122:125], v[160:163], v[184:187], v[122:125]
	v_mfma_f32_16x16x32_bf16 v[118:121], v[152:155], v[192:195], v[118:121]
	v_mfma_f32_16x16x32_bf16 v[114:117], v[160:163], v[192:195], v[114:117]
	v_mfma_f32_16x16x32_bf16 v[102:105], v[152:155], v[200:203], v[102:105]
	v_mfma_f32_16x16x32_bf16 v[98:101], v[160:163], v[200:203], v[98:101]
	v_mfma_f32_16x16x32_bf16 v[86:89], v[152:155], v[208:211], v[86:89]
	v_mfma_f32_16x16x32_bf16 v[82:85], v[160:163], v[208:211], v[82:85]
	v_mfma_f32_16x16x32_bf16 v[126:129], v[156:159], v[188:191], v[126:129]
	v_mfma_f32_16x16x32_bf16 v[122:125], v[164:167], v[188:191], v[122:125]
	v_mfma_f32_16x16x32_bf16 v[118:121], v[156:159], v[196:199], v[118:121]
	v_mfma_f32_16x16x32_bf16 v[114:117], v[164:167], v[196:199], v[114:117]
	v_mfma_f32_16x16x32_bf16 v[102:105], v[156:159], v[204:207], v[102:105]
	v_mfma_f32_16x16x32_bf16 v[98:101], v[164:167], v[204:207], v[98:101]
	v_mfma_f32_16x16x32_bf16 v[86:89], v[156:159], v[212:215], v[86:89]
	v_mfma_f32_16x16x32_bf16 v[82:85], v[164:167], v[212:215], v[82:85]
	v_mfma_f32_16x16x32_bf16 v[110:113], v[168:171], v[184:187], v[110:113]
	v_mfma_f32_16x16x32_bf16 v[106:109], v[176:179], v[184:187], v[106:109]
	v_mfma_f32_16x16x32_bf16 v[94:97], v[168:171], v[192:195], v[94:97]
	v_mfma_f32_16x16x32_bf16 v[90:93], v[176:179], v[192:195], v[90:93]
	v_mfma_f32_16x16x32_bf16 v[78:81], v[168:171], v[200:203], v[78:81]
	v_mfma_f32_16x16x32_bf16 v[74:77], v[176:179], v[200:203], v[74:77]
	v_mfma_f32_16x16x32_bf16 v[70:73], v[168:171], v[208:211], v[70:73]
	v_mfma_f32_16x16x32_bf16 v[66:69], v[176:179], v[208:211], v[66:69]
	v_mfma_f32_16x16x32_bf16 v[110:113], v[172:175], v[188:191], v[110:113]
	v_mfma_f32_16x16x32_bf16 v[106:109], v[180:183], v[188:191], v[106:109]
	v_mfma_f32_16x16x32_bf16 v[94:97], v[172:175], v[196:199], v[94:97]
	v_mfma_f32_16x16x32_bf16 v[90:93], v[180:183], v[196:199], v[90:93]
	v_mfma_f32_16x16x32_bf16 v[78:81], v[172:175], v[204:207], v[78:81]
	v_mfma_f32_16x16x32_bf16 v[74:77], v[180:183], v[204:207], v[74:77]
	v_mfma_f32_16x16x32_bf16 v[70:73], v[172:175], v[212:215], v[70:73]
	v_mfma_f32_16x16x32_bf16 v[66:69], v[180:183], v[212:215], v[66:69]
	s_barrier
	s_add_i32 s40, s64, s47
	v_lshl_add_u64 v[216:217], v[216:217], 0, s[12:13]
	s_mov_b32 m0, s40
	ds_read_b128 v[184:187], v150 offset:49152
	ds_read_b128 v[188:191], v150 offset:50176
	ds_read_b128 v[192:195], v150 offset:51200
	ds_read_b128 v[196:199], v150 offset:52224
	ds_read_b128 v[200:203], v150 offset:53248
	ds_read_b128 v[204:207], v150 offset:54272
	ds_read_b128 v[208:211], v150 offset:55296
	ds_read_b128 v[212:215], v150 offset:56320
	global_load_lds_dwordx4 v[216:217], off
	s_add_i32 m0, s40, 0x2000
	s_add_u32 s38, s38, 0x40080
	v_lshl_add_u64 v[216:217], v[218:219], 0, s[12:13]
	s_addc_u32 s39, s39, 0
	s_add_i32 s40, s65, s47
	global_load_lds_dwordx4 v[216:217], off
	v_lshl_add_u64 v[216:217], s[38:39], 0, v[132:133]
	s_mov_b32 m0, s40
	s_nop 0
	global_load_lds_dwordx4 v[216:217], off
	v_lshl_add_u64 v[216:217], s[38:39], 0, v[136:137]
	s_add_i32 m0, s40, 0x2000
	s_nop 0
	global_load_lds_dwordx4 v[216:217], off
	v_lshl_add_u64 v[216:217], v[220:221], 0, s[12:13]
	s_mov_b32 m0, s52
	s_nop 0
	global_load_lds_dwordx4 v[216:217], off
	v_lshl_add_u64 v[216:217], v[222:223], 0, s[12:13]
	s_mov_b32 m0, s53
	s_nop 0
	global_load_lds_dwordx4 v[216:217], off
	s_waitcnt vmcnt(8)
	s_waitcnt lgkmcnt(0)
	s_barrier
	s_waitcnt lgkmcnt(0)
	v_mfma_f32_16x16x32_bf16 v[62:65], v[152:155], v[184:187], v[62:65]
	v_mfma_f32_16x16x32_bf16 v[58:61], v[160:163], v[184:187], v[58:61]
	v_mfma_f32_16x16x32_bf16 v[54:57], v[152:155], v[192:195], v[54:57]
	v_mfma_f32_16x16x32_bf16 v[50:53], v[160:163], v[192:195], v[50:53]
	v_mfma_f32_16x16x32_bf16 v[38:41], v[152:155], v[200:203], v[38:41]
	v_mfma_f32_16x16x32_bf16 v[34:37], v[160:163], v[200:203], v[34:37]
	v_mfma_f32_16x16x32_bf16 v[22:25], v[152:155], v[208:211], v[22:25]
	v_mfma_f32_16x16x32_bf16 v[18:21], v[160:163], v[208:211], v[18:21]
	v_mfma_f32_16x16x32_bf16 v[62:65], v[156:159], v[188:191], v[62:65]
	v_mfma_f32_16x16x32_bf16 v[58:61], v[164:167], v[188:191], v[58:61]
	v_mfma_f32_16x16x32_bf16 v[54:57], v[156:159], v[196:199], v[54:57]
	v_mfma_f32_16x16x32_bf16 v[50:53], v[164:167], v[196:199], v[50:53]
	v_mfma_f32_16x16x32_bf16 v[38:41], v[156:159], v[204:207], v[38:41]
	v_mfma_f32_16x16x32_bf16 v[34:37], v[164:167], v[204:207], v[34:37]
	v_mfma_f32_16x16x32_bf16 v[22:25], v[156:159], v[212:215], v[22:25]
	v_mfma_f32_16x16x32_bf16 v[18:21], v[164:167], v[212:215], v[18:21]
	v_mfma_f32_16x16x32_bf16 v[46:49], v[168:171], v[184:187], v[46:49]
	v_mfma_f32_16x16x32_bf16 v[42:45], v[176:179], v[184:187], v[42:45]
	v_mfma_f32_16x16x32_bf16 v[30:33], v[168:171], v[192:195], v[30:33]
	v_mfma_f32_16x16x32_bf16 v[26:29], v[176:179], v[192:195], v[26:29]
	v_mfma_f32_16x16x32_bf16 v[14:17], v[168:171], v[200:203], v[14:17]
	v_mfma_f32_16x16x32_bf16 v[10:13], v[176:179], v[200:203], v[10:13]
	v_mfma_f32_16x16x32_bf16 v[6:9], v[168:171], v[208:211], v[6:9]
	v_mfma_f32_16x16x32_bf16 v[2:5], v[176:179], v[208:211], v[2:5]
	v_mfma_f32_16x16x32_bf16 v[46:49], v[172:175], v[188:191], v[46:49]
	v_mfma_f32_16x16x32_bf16 v[42:45], v[180:183], v[188:191], v[42:45]
	v_mfma_f32_16x16x32_bf16 v[30:33], v[172:175], v[196:199], v[30:33]
	v_mfma_f32_16x16x32_bf16 v[26:29], v[180:183], v[196:199], v[26:29]
	v_mfma_f32_16x16x32_bf16 v[14:17], v[172:175], v[204:207], v[14:17]
	v_mfma_f32_16x16x32_bf16 v[10:13], v[180:183], v[204:207], v[10:13]
	v_mfma_f32_16x16x32_bf16 v[6:9], v[172:175], v[212:215], v[6:9]
	v_mfma_f32_16x16x32_bf16 v[2:5], v[180:183], v[212:215], v[2:5]
	s_barrier
	s_add_i32 s63, s63, 2
	s_add_u32 s36, s36, 0x100
	s_addc_u32 s37, s37, 0
	s_add_u32 s29, s29, 0x100
	s_addc_u32 s62, s62, 0
	s_cmp_gt_u32 s63, 13
	s_cbranch_scc0 .LBB0_576
	s_and_b64 vcc, exec, s[14:15]
	s_cbranch_vccz .LBB0_579
	s_barrier

.LBB0_645:
	ds_read_b128 v[154:157], v150
	ds_read_b128 v[158:161], v150 offset:1024
	ds_read_b128 v[162:165], v150 offset:2048
	ds_read_b128 v[166:169], v150 offset:3072
	ds_read_b128 v[170:173], v151
	ds_read_b128 v[174:177], v151 offset:1024
	ds_read_b128 v[178:181], v151 offset:2048
	ds_read_b128 v[182:185], v151 offset:3072
	s_add_u32 s28, s26, 0xfffc0080
	s_addc_u32 s29, s27, -1
	s_cmp_eq_u32 s53, 12
	s_cselect_b32 s31, s10, s29
	s_cselect_b32 s30, s17, s28
	s_cselect_b32 s29, s15, s52
	s_cselect_b32 s28, s20, s21
	v_lshl_add_u64 v[146:147], s[26:27], 0, v[138:139]
	s_add_i32 m0, s25, 0xc000
	ds_read_b128 v[186:189], v152
	ds_read_b128 v[190:193], v152 offset:1024
	ds_read_b128 v[194:197], v152 offset:2048
	ds_read_b128 v[198:201], v152 offset:3072
	ds_read_b128 v[202:205], v152 offset:4096
	ds_read_b128 v[206:209], v152 offset:5120
	ds_read_b128 v[210:213], v152 offset:6144
	ds_read_b128 v[214:217], v152 offset:7168
	global_load_lds_dwordx4 v[146:147], off
	v_lshl_add_u64 v[146:147], s[26:27], 0, v[140:141]
	s_add_i32 m0, s25, 0xe000
	s_nop 0
	global_load_lds_dwordx4 v[146:147], off
	s_waitcnt vmcnt(8)
	s_waitcnt lgkmcnt(0)
	s_barrier
	s_waitcnt lgkmcnt(0)
	v_mfma_f32_16x16x32_bf16 v[126:129], v[154:157], v[186:189], v[126:129]
	v_mfma_f32_16x16x32_bf16 v[122:125], v[162:165], v[186:189], v[122:125]
	v_mfma_f32_16x16x32_bf16 v[110:113], v[154:157], v[194:197], v[110:113]
	v_mfma_f32_16x16x32_bf16 v[106:109], v[162:165], v[194:197], v[106:109]
	v_mfma_f32_16x16x32_bf16 v[94:97], v[154:157], v[202:205], v[94:97]
	v_mfma_f32_16x16x32_bf16 v[90:93], v[162:165], v[202:205], v[90:93]
	v_mfma_f32_16x16x32_bf16 v[78:81], v[154:157], v[210:213], v[78:81]
	v_mfma_f32_16x16x32_bf16 v[74:77], v[162:165], v[210:213], v[74:77]
	v_mfma_f32_16x16x32_bf16 v[126:129], v[158:161], v[190:193], v[126:129]
	v_mfma_f32_16x16x32_bf16 v[122:125], v[166:169], v[190:193], v[122:125]
	v_mfma_f32_16x16x32_bf16 v[110:113], v[158:161], v[198:201], v[110:113]
	v_mfma_f32_16x16x32_bf16 v[106:109], v[166:169], v[198:201], v[106:109]
	v_mfma_f32_16x16x32_bf16 v[94:97], v[158:161], v[206:209], v[94:97]
	v_mfma_f32_16x16x32_bf16 v[90:93], v[166:169], v[206:209], v[90:93]
	v_mfma_f32_16x16x32_bf16 v[78:81], v[158:161], v[214:217], v[78:81]
	v_mfma_f32_16x16x32_bf16 v[74:77], v[166:169], v[214:217], v[74:77]
	v_mfma_f32_16x16x32_bf16 v[118:121], v[170:173], v[186:189], v[118:121]
	v_mfma_f32_16x16x32_bf16 v[114:117], v[178:181], v[186:189], v[114:117]
	v_mfma_f32_16x16x32_bf16 v[102:105], v[170:173], v[194:197], v[102:105]
	v_mfma_f32_16x16x32_bf16 v[98:101], v[178:181], v[194:197], v[98:101]
	v_mfma_f32_16x16x32_bf16 v[86:89], v[170:173], v[202:205], v[86:89]
	v_mfma_f32_16x16x32_bf16 v[82:85], v[178:181], v[202:205], v[82:85]
	v_mfma_f32_16x16x32_bf16 v[70:73], v[170:173], v[210:213], v[70:73]
	v_mfma_f32_16x16x32_bf16 v[66:69], v[178:181], v[210:213], v[66:69]
	v_mfma_f32_16x16x32_bf16 v[118:121], v[174:177], v[190:193], v[118:121]
	v_mfma_f32_16x16x32_bf16 v[114:117], v[182:185], v[190:193], v[114:117]
	v_mfma_f32_16x16x32_bf16 v[102:105], v[174:177], v[198:201], v[102:105]
	v_mfma_f32_16x16x32_bf16 v[98:101], v[182:185], v[198:201], v[98:101]
	v_mfma_f32_16x16x32_bf16 v[86:89], v[174:177], v[206:209], v[86:89]
	v_mfma_f32_16x16x32_bf16 v[82:85], v[182:185], v[206:209], v[82:85]
	v_mfma_f32_16x16x32_bf16 v[70:73], v[174:177], v[214:217], v[70:73]
	v_mfma_f32_16x16x32_bf16 v[66:69], v[182:185], v[214:217], v[66:69]
	s_barrier
	s_add_i32 s54, s48, s38
	v_lshl_add_u64 v[146:147], s[28:29], 0, v[134:135]
	s_mov_b32 m0, s54
	ds_read_b128 v[186:189], v152 offset:16384
	ds_read_b128 v[190:193], v152 offset:17408
	ds_read_b128 v[194:197], v152 offset:18432
	ds_read_b128 v[198:201], v152 offset:19456
	ds_read_b128 v[202:205], v152 offset:20480
	ds_read_b128 v[206:209], v152 offset:21504
	ds_read_b128 v[210:213], v152 offset:22528
	ds_read_b128 v[214:217], v152 offset:23552
	global_load_lds_dwordx4 v[146:147], off
	s_add_i32 m0, s54, 0x2000
	s_add_u32 s54, s28, 0x40000
	v_lshl_add_u64 v[218:219], s[28:29], 0, v[130:131]
	s_addc_u32 s55, s29, 0
	s_add_i32 s56, s49, s38
	global_load_lds_dwordx4 v[218:219], off
	v_lshl_add_u64 v[220:221], s[54:55], 0, v[134:135]
	s_mov_b32 m0, s56
	v_lshl_add_u64 v[222:223], s[30:31], 0, v[132:133]
	global_load_lds_dwordx4 v[220:221], off
	v_lshl_add_u64 v[220:221], s[54:55], 0, v[130:131]
	s_add_i32 m0, s56, 0x2000
	s_nop 0
	global_load_lds_dwordx4 v[220:221], off
	v_lshl_add_u64 v[220:221], s[30:31], 0, v[136:137]
	s_mov_b32 m0, s25
	s_nop 0
	global_load_lds_dwordx4 v[220:221], off
	s_mov_b32 m0, s41
	s_nop 0
	global_load_lds_dwordx4 v[222:223], off
	s_waitcnt vmcnt(8)
	s_waitcnt lgkmcnt(0)
	s_barrier
	s_waitcnt lgkmcnt(0)
	v_mfma_f32_16x16x32_bf16 v[62:65], v[154:157], v[186:189], v[62:65]
	v_mfma_f32_16x16x32_bf16 v[58:61], v[162:165], v[186:189], v[58:61]
	v_mfma_f32_16x16x32_bf16 v[46:49], v[154:157], v[194:197], v[46:49]
	v_mfma_f32_16x16x32_bf16 v[42:45], v[162:165], v[194:197], v[42:45]
	v_mfma_f32_16x16x32_bf16 v[30:33], v[154:157], v[202:205], v[30:33]
	v_mfma_f32_16x16x32_bf16 v[26:29], v[162:165], v[202:205], v[26:29]
	v_mfma_f32_16x16x32_bf16 v[14:17], v[154:157], v[210:213], v[14:17]
	v_mfma_f32_16x16x32_bf16 v[10:13], v[162:165], v[210:213], v[10:13]
	v_mfma_f32_16x16x32_bf16 v[62:65], v[158:161], v[190:193], v[62:65]
	v_mfma_f32_16x16x32_bf16 v[58:61], v[166:169], v[190:193], v[58:61]
	v_mfma_f32_16x16x32_bf16 v[46:49], v[158:161], v[198:201], v[46:49]
	v_mfma_f32_16x16x32_bf16 v[42:45], v[166:169], v[198:201], v[42:45]
	v_mfma_f32_16x16x32_bf16 v[30:33], v[158:161], v[206:209], v[30:33]
	v_mfma_f32_16x16x32_bf16 v[26:29], v[166:169], v[206:209], v[26:29]
	v_mfma_f32_16x16x32_bf16 v[14:17], v[158:161], v[214:217], v[14:17]
	v_mfma_f32_16x16x32_bf16 v[10:13], v[166:169], v[214:217], v[10:13]
	v_mfma_f32_16x16x32_bf16 v[54:57], v[170:173], v[186:189], v[54:57]
	v_mfma_f32_16x16x32_bf16 v[50:53], v[178:181], v[186:189], v[50:53]
	v_mfma_f32_16x16x32_bf16 v[38:41], v[170:173], v[194:197], v[38:41]
	v_mfma_f32_16x16x32_bf16 v[34:37], v[178:181], v[194:197], v[34:37]
	v_mfma_f32_16x16x32_bf16 v[22:25], v[170:173], v[202:205], v[22:25]
	v_mfma_f32_16x16x32_bf16 v[18:21], v[178:181], v[202:205], v[18:21]
	v_mfma_f32_16x16x32_bf16 v[6:9], v[170:173], v[210:213], v[6:9]
	v_mfma_f32_16x16x32_bf16 v[2:5], v[178:181], v[210:213], v[2:5]
	v_mfma_f32_16x16x32_bf16 v[54:57], v[174:177], v[190:193], v[54:57]
	v_mfma_f32_16x16x32_bf16 v[50:53], v[182:185], v[190:193], v[50:53]
	v_mfma_f32_16x16x32_bf16 v[38:41], v[174:177], v[198:201], v[38:41]
	v_mfma_f32_16x16x32_bf16 v[34:37], v[182:185], v[198:201], v[34:37]
	v_mfma_f32_16x16x32_bf16 v[22:25], v[174:177], v[206:209], v[22:25]
	v_mfma_f32_16x16x32_bf16 v[18:21], v[182:185], v[206:209], v[18:21]
	v_mfma_f32_16x16x32_bf16 v[6:9], v[174:177], v[214:217], v[6:9]
	v_mfma_f32_16x16x32_bf16 v[2:5], v[182:185], v[214:217], v[2:5]
	s_barrier
	s_add_i32 s54, 0, 0x18000
	v_add_u32_e32 v153, s54, v148
	s_add_i32 s55, 0, 0x1c000
	ds_read_b128 v[154:157], v153
	ds_read_b128 v[158:161], v153 offset:1024
	ds_read_b128 v[162:165], v153 offset:2048
	ds_read_b128 v[166:169], v153 offset:3072
	v_add_u32_e32 v153, s55, v148
	ds_read_b128 v[170:173], v153
	ds_read_b128 v[174:177], v153 offset:1024
	ds_read_b128 v[178:181], v153 offset:2048
	ds_read_b128 v[182:185], v153 offset:3072
	s_add_u32 s30, s30, 0x40000
	s_addc_u32 s31, s31, 0
	s_mov_b32 m0, s42
	v_lshl_add_u64 v[224:225], s[30:31], 0, v[136:137]
	ds_read_b128 v[186:189], v152 offset:32768
	ds_read_b128 v[190:193], v152 offset:33792
	ds_read_b128 v[194:197], v152 offset:34816
	ds_read_b128 v[198:201], v152 offset:35840
	ds_read_b128 v[202:205], v152 offset:36864
	ds_read_b128 v[206:209], v152 offset:37888
	ds_read_b128 v[210:213], v152 offset:38912
	ds_read_b128 v[214:217], v152 offset:39936
	global_load_lds_dwordx4 v[224:225], off
	v_lshl_add_u64 v[224:225], s[30:31], 0, v[132:133]
	s_mov_b32 m0, s43
	s_nop 0
	global_load_lds_dwordx4 v[224:225], off
	s_waitcnt vmcnt(8)
	s_waitcnt lgkmcnt(0)
	s_barrier
	s_waitcnt lgkmcnt(0)
	v_mfma_f32_16x16x32_bf16 v[126:129], v[154:157], v[186:189], v[126:129]
	v_mfma_f32_16x16x32_bf16 v[122:125], v[162:165], v[186:189], v[122:125]
	v_mfma_f32_16x16x32_bf16 v[110:113], v[154:157], v[194:197], v[110:113]
	v_mfma_f32_16x16x32_bf16 v[106:109], v[162:165], v[194:197], v[106:109]
	v_mfma_f32_16x16x32_bf16 v[94:97], v[154:157], v[202:205], v[94:97]
	v_mfma_f32_16x16x32_bf16 v[90:93], v[162:165], v[202:205], v[90:93]
	v_mfma_f32_16x16x32_bf16 v[78:81], v[154:157], v[210:213], v[78:81]
	v_mfma_f32_16x16x32_bf16 v[74:77], v[162:165], v[210:213], v[74:77]
	v_mfma_f32_16x16x32_bf16 v[126:129], v[158:161], v[190:193], v[126:129]
	v_mfma_f32_16x16x32_bf16 v[122:125], v[166:169], v[190:193], v[122:125]
	v_mfma_f32_16x16x32_bf16 v[110:113], v[158:161], v[198:201], v[110:113]
	v_mfma_f32_16x16x32_bf16 v[106:109], v[166:169], v[198:201], v[106:109]
	v_mfma_f32_16x16x32_bf16 v[94:97], v[158:161], v[206:209], v[94:97]
	v_mfma_f32_16x16x32_bf16 v[90:93], v[166:169], v[206:209], v[90:93]
	v_mfma_f32_16x16x32_bf16 v[78:81], v[158:161], v[214:217], v[78:81]
	v_mfma_f32_16x16x32_bf16 v[74:77], v[166:169], v[214:217], v[74:77]
	v_mfma_f32_16x16x32_bf16 v[118:121], v[170:173], v[186:189], v[118:121]
	v_mfma_f32_16x16x32_bf16 v[114:117], v[178:181], v[186:189], v[114:117]
	v_mfma_f32_16x16x32_bf16 v[102:105], v[170:173], v[194:197], v[102:105]
	v_mfma_f32_16x16x32_bf16 v[98:101], v[178:181], v[194:197], v[98:101]
	v_mfma_f32_16x16x32_bf16 v[86:89], v[170:173], v[202:205], v[86:89]
	v_mfma_f32_16x16x32_bf16 v[82:85], v[178:181], v[202:205], v[82:85]
	v_mfma_f32_16x16x32_bf16 v[70:73], v[170:173], v[210:213], v[70:73]
	v_mfma_f32_16x16x32_bf16 v[66:69], v[178:181], v[210:213], v[66:69]
	v_mfma_f32_16x16x32_bf16 v[118:121], v[174:177], v[190:193], v[118:121]
	v_mfma_f32_16x16x32_bf16 v[114:117], v[182:185], v[190:193], v[114:117]
	v_mfma_f32_16x16x32_bf16 v[102:105], v[174:177], v[198:201], v[102:105]
	v_mfma_f32_16x16x32_bf16 v[98:101], v[182:185], v[198:201], v[98:101]
	v_mfma_f32_16x16x32_bf16 v[86:89], v[174:177], v[206:209], v[86:89]
	v_mfma_f32_16x16x32_bf16 v[82:85], v[182:185], v[206:209], v[82:85]
	v_mfma_f32_16x16x32_bf16 v[70:73], v[174:177], v[214:217], v[70:73]
	v_mfma_f32_16x16x32_bf16 v[66:69], v[182:185], v[214:217], v[66:69]
	s_barrier
	s_add_i32 s30, s54, s38
	v_lshl_add_u64 v[146:147], v[146:147], 0, s[8:9]
	s_mov_b32 m0, s30
	ds_read_b128 v[186:189], v152 offset:49152
	ds_read_b128 v[190:193], v152 offset:50176
	ds_read_b128 v[194:197], v152 offset:51200
	ds_read_b128 v[198:201], v152 offset:52224
	ds_read_b128 v[202:205], v152 offset:53248
	ds_read_b128 v[206:209], v152 offset:54272
	ds_read_b128 v[210:213], v152 offset:55296
	ds_read_b128 v[214:217], v152 offset:56320
	global_load_lds_dwordx4 v[146:147], off
	s_add_i32 m0, s30, 0x2000
	s_add_u32 s28, s28, 0x40080
	v_lshl_add_u64 v[146:147], v[218:219], 0, s[8:9]
	s_addc_u32 s29, s29, 0
	s_add_i32 s30, s55, s38
	global_load_lds_dwordx4 v[146:147], off
	v_lshl_add_u64 v[146:147], s[28:29], 0, v[134:135]
	s_mov_b32 m0, s30
	s_nop 0
	global_load_lds_dwordx4 v[146:147], off
	v_lshl_add_u64 v[146:147], s[28:29], 0, v[130:131]
	s_add_i32 m0, s30, 0x2000
	s_nop 0
	global_load_lds_dwordx4 v[146:147], off
	v_lshl_add_u64 v[146:147], v[220:221], 0, s[8:9]
	s_mov_b32 m0, s45
	s_nop 0
	global_load_lds_dwordx4 v[146:147], off
	v_lshl_add_u64 v[146:147], v[222:223], 0, s[8:9]
	s_mov_b32 m0, s46
	s_nop 0
	global_load_lds_dwordx4 v[146:147], off
	s_waitcnt vmcnt(8)
	s_waitcnt lgkmcnt(0)
	s_barrier
	s_waitcnt lgkmcnt(0)
	v_mfma_f32_16x16x32_bf16 v[62:65], v[154:157], v[186:189], v[62:65]
	v_mfma_f32_16x16x32_bf16 v[58:61], v[162:165], v[186:189], v[58:61]
	v_mfma_f32_16x16x32_bf16 v[46:49], v[154:157], v[194:197], v[46:49]
	v_mfma_f32_16x16x32_bf16 v[42:45], v[162:165], v[194:197], v[42:45]
	v_mfma_f32_16x16x32_bf16 v[30:33], v[154:157], v[202:205], v[30:33]
	v_mfma_f32_16x16x32_bf16 v[26:29], v[162:165], v[202:205], v[26:29]
	v_mfma_f32_16x16x32_bf16 v[14:17], v[154:157], v[210:213], v[14:17]
	v_mfma_f32_16x16x32_bf16 v[10:13], v[162:165], v[210:213], v[10:13]
	v_mfma_f32_16x16x32_bf16 v[62:65], v[158:161], v[190:193], v[62:65]
	v_mfma_f32_16x16x32_bf16 v[58:61], v[166:169], v[190:193], v[58:61]
	v_mfma_f32_16x16x32_bf16 v[46:49], v[158:161], v[198:201], v[46:49]
	v_mfma_f32_16x16x32_bf16 v[42:45], v[166:169], v[198:201], v[42:45]
	v_mfma_f32_16x16x32_bf16 v[30:33], v[158:161], v[206:209], v[30:33]
	v_mfma_f32_16x16x32_bf16 v[26:29], v[166:169], v[206:209], v[26:29]
	v_mfma_f32_16x16x32_bf16 v[14:17], v[158:161], v[214:217], v[14:17]
	v_mfma_f32_16x16x32_bf16 v[10:13], v[166:169], v[214:217], v[10:13]
	v_mfma_f32_16x16x32_bf16 v[54:57], v[170:173], v[186:189], v[54:57]
	v_mfma_f32_16x16x32_bf16 v[50:53], v[178:181], v[186:189], v[50:53]
	v_mfma_f32_16x16x32_bf16 v[38:41], v[170:173], v[194:197], v[38:41]
	v_mfma_f32_16x16x32_bf16 v[34:37], v[178:181], v[194:197], v[34:37]
	v_mfma_f32_16x16x32_bf16 v[22:25], v[170:173], v[202:205], v[22:25]
	v_mfma_f32_16x16x32_bf16 v[18:21], v[178:181], v[202:205], v[18:21]
	v_mfma_f32_16x16x32_bf16 v[6:9], v[170:173], v[210:213], v[6:9]
	v_mfma_f32_16x16x32_bf16 v[2:5], v[178:181], v[210:213], v[2:5]
	v_mfma_f32_16x16x32_bf16 v[54:57], v[174:177], v[190:193], v[54:57]
	v_mfma_f32_16x16x32_bf16 v[50:53], v[182:185], v[190:193], v[50:53]
	v_mfma_f32_16x16x32_bf16 v[38:41], v[174:177], v[198:201], v[38:41]
	v_mfma_f32_16x16x32_bf16 v[34:37], v[182:185], v[198:201], v[34:37]
	v_mfma_f32_16x16x32_bf16 v[22:25], v[174:177], v[206:209], v[22:25]
	v_mfma_f32_16x16x32_bf16 v[18:21], v[182:185], v[206:209], v[18:21]
	v_mfma_f32_16x16x32_bf16 v[6:9], v[174:177], v[214:217], v[6:9]
	v_mfma_f32_16x16x32_bf16 v[2:5], v[182:185], v[214:217], v[2:5]
	s_barrier
	s_add_i32 s53, s53, 2
	s_add_u32 s26, s26, 0x100
	s_addc_u32 s27, s27, 0
	s_add_u32 s21, s21, 0x100
	s_addc_u32 s52, s52, 0
	s_cmp_gt_u32 s53, 13
	s_cbranch_scc0 .LBB0_645
	s_and_b64 vcc, exec, s[12:13]
	s_cbranch_vccz .LBB0_648
	s_barrier
